# SwiGLU epilogue fma form; fused epilogue gain+residual loads hoisted above exchange; conv phase loads all rows up front
# speedup vs baseline: 1.0054x; 1.0050x over previous
.LBB0_60:
	v_lshl_add_u32 v18, s11, 6, v56
	v_and_b32_e32 v1, 0xff0, v18
	v_cmp_ne_u32_e32 vcc, 0, v1
	v_mov_b32_e32 v26, v0
	v_mov_b32_e32 v27, v0
	v_mov_b32_e32 v28, v0
	v_mov_b32_e32 v29, v0
	v_mov_b32_e32 v30, v0
	v_mov_b32_e32 v31, v0
	v_mov_b32_e32 v32, v0
	v_mov_b32_e32 v33, v0
	s_and_saveexec_b64 s[8:9], vcc
	s_cbranch_execz .LBB0_62
	v_ashrrev_i32_e32 v19, 31, v18
	v_lshlrev_b64 v[2:3], 11, v[18:19]
	v_lshl_add_u64 v[2:3], v[38:39], 0, v[2:3]
	global_load_dwordx4 v[26:29], v[2:3], off offset:-4096
	global_load_dwordx4 v[30:33], v[2:3], off offset:-2048
.LBB0_62:
	s_or_b64 exec, exec, s[8:9]
	v_lshl_add_u32 v54, v18, 11, v58
	v_mov_b32_e32 v55, v54
	global_load_dwordx4 v[64:67], v54, s[82:83]
	global_load_dwordx4 v[68:71], v54, s[84:85]
	global_load_dwordx4 v[72:75], v54, s[82:83] offset:2048
	global_load_dwordx4 v[76:79], v54, s[84:85] offset:2048
	v_add_u32_e32 v54, 0x1000, v54
	global_load_dwordx4 v[80:83], v54, s[82:83]
	global_load_dwordx4 v[84:87], v54, s[84:85]
	global_load_dwordx4 v[88:91], v54, s[82:83] offset:2048
	global_load_dwordx4 v[92:95], v54, s[84:85] offset:2048
	v_add_u32_e32 v54, 0x1000, v54
	global_load_dwordx4 v[96:99], v54, s[82:83]
	global_load_dwordx4 v[100:103], v54, s[84:85]
	global_load_dwordx4 v[104:107], v54, s[82:83] offset:2048
	global_load_dwordx4 v[108:111], v54, s[84:85] offset:2048
	v_add_u32_e32 v54, 0x1000, v54
	global_load_dwordx4 v[112:115], v54, s[82:83]
	global_load_dwordx4 v[116:119], v54, s[84:85]
	global_load_dwordx4 v[120:123], v54, s[82:83] offset:2048
	global_load_dwordx4 v[124:127], v54, s[84:85] offset:2048
	v_add_u32_e32 v54, 0x1000, v54
	global_load_dwordx4 v[128:131], v54, s[82:83]
	global_load_dwordx4 v[132:135], v54, s[84:85]
	global_load_dwordx4 v[136:139], v54, s[82:83] offset:2048
	global_load_dwordx4 v[140:143], v54, s[84:85] offset:2048
	v_add_u32_e32 v54, 0x1000, v54
	global_load_dwordx4 v[144:147], v54, s[82:83]
	global_load_dwordx4 v[148:151], v54, s[84:85]
	global_load_dwordx4 v[152:155], v54, s[82:83] offset:2048
	global_load_dwordx4 v[156:159], v54, s[84:85] offset:2048
	v_add_u32_e32 v54, 0x1000, v54
	global_load_dwordx4 v[160:163], v54, s[82:83]
	global_load_dwordx4 v[164:167], v54, s[84:85]
	global_load_dwordx4 v[168:171], v54, s[82:83] offset:2048
	global_load_dwordx4 v[172:175], v54, s[84:85] offset:2048
	v_add_u32_e32 v54, 0x1000, v54
	global_load_dwordx4 v[176:179], v54, s[82:83]
	global_load_dwordx4 v[180:183], v54, s[84:85]
	global_load_dwordx4 v[184:187], v54, s[82:83] offset:2048
	global_load_dwordx4 v[188:191], v54, s[84:85] offset:2048
	s_waitcnt vmcnt(30)
	v_lshlrev_b32_e32 v192, 16, v26
	v_lshlrev_b32_e32 v193, 16, v27
	v_and_b32_e32 v194, s33, v26
	v_and_b32_e32 v195, s33, v27
	v_lshlrev_b32_e32 v196, 16, v28
	v_lshlrev_b32_e32 v197, 16, v29
	v_and_b32_e32 v198, s33, v28
	v_and_b32_e32 v199, s33, v29
	v_lshlrev_b32_e32 v200, 16, v30
	v_lshlrev_b32_e32 v201, 16, v31
	v_and_b32_e32 v202, s33, v30
	v_and_b32_e32 v203, s33, v31
	v_lshlrev_b32_e32 v204, 16, v32
	v_lshlrev_b32_e32 v205, 16, v33
	v_and_b32_e32 v206, s33, v32
	v_and_b32_e32 v207, s33, v33
	v_lshlrev_b32_e32 v236, 16, v64
	v_lshlrev_b32_e32 v237, 16, v65
	v_and_b32_e32 v238, s33, v64
	v_and_b32_e32 v239, s33, v65
	v_lshlrev_b32_e32 v240, 16, v66
	v_lshlrev_b32_e32 v241, 16, v67
	v_and_b32_e32 v242, s33, v66
	v_and_b32_e32 v243, s33, v67
	v_lshlrev_b32_e32 v244, 16, v68
	v_lshlrev_b32_e32 v245, 16, v69
	v_and_b32_e32 v246, s33, v68
	v_and_b32_e32 v247, s33, v69
	v_lshlrev_b32_e32 v248, 16, v70
	v_lshlrev_b32_e32 v249, 16, v71
	v_and_b32_e32 v250, s33, v70
	v_and_b32_e32 v251, s33, v71
	v_pk_mul_f32 v[46:47], v[10:11], v[200:201]
	v_pk_mul_f32 v[48:49], v[20:21], v[202:203]
	v_pk_mul_f32 v[50:51], v[42:43], v[204:205]
	v_pk_mul_f32 v[52:53], v[12:13], v[206:207]
	v_pk_fma_f32 v[46:47], v[40:41], v[192:193], v[46:47]
	v_pk_fma_f32 v[48:49], v[8:9], v[194:195], v[48:49]
	v_pk_fma_f32 v[50:51], v[6:7], v[196:197], v[50:51]
	v_pk_fma_f32 v[52:53], v[4:5], v[198:199], v[52:53]
	v_pk_fma_f32 v[46:47], v[14:15], v[236:237], v[46:47]
	v_pk_fma_f32 v[48:49], v[24:25], v[238:239], v[48:49]
	v_pk_fma_f32 v[50:51], v[44:45], v[240:241], v[50:51]
	v_pk_fma_f32 v[52:53], v[16:17], v[242:243], v[52:53]
	v_pk_mul_f32 v[46:47], v[46:47], v[244:245]
	v_pk_mul_f32 v[48:49], v[48:49], v[246:247]
	v_pk_mul_f32 v[50:51], v[50:51], v[248:249]
	v_pk_mul_f32 v[52:53], v[52:53], v[250:251]
	v_cvt_pk_bf16_f32 v60, v46, v48
	v_cvt_pk_bf16_f32 v61, v47, v49
	v_cvt_pk_bf16_f32 v62, v50, v52
	v_cvt_pk_bf16_f32 v63, v51, v53
	global_store_dwordx4 v55, v[60:63], s[90:91] sc1
	s_nop 1
	s_waitcnt vmcnt(29)
	v_lshlrev_b32_e32 v192, 16, v72
	v_lshlrev_b32_e32 v193, 16, v73
	v_and_b32_e32 v194, s33, v72
	v_and_b32_e32 v195, s33, v73
	v_lshlrev_b32_e32 v196, 16, v74
	v_lshlrev_b32_e32 v197, 16, v75
	v_and_b32_e32 v198, s33, v74
	v_and_b32_e32 v199, s33, v75
	v_lshlrev_b32_e32 v244, 16, v76
	v_lshlrev_b32_e32 v245, 16, v77
	v_and_b32_e32 v246, s33, v76
	v_and_b32_e32 v247, s33, v77
	v_lshlrev_b32_e32 v248, 16, v78
	v_lshlrev_b32_e32 v249, 16, v79
	v_and_b32_e32 v250, s33, v78
	v_and_b32_e32 v251, s33, v79
	v_pk_mul_f32 v[46:47], v[10:11], v[236:237]
	v_pk_mul_f32 v[48:49], v[20:21], v[238:239]
	v_pk_mul_f32 v[50:51], v[42:43], v[240:241]
	v_pk_mul_f32 v[52:53], v[12:13], v[242:243]
	v_pk_fma_f32 v[46:47], v[40:41], v[200:201], v[46:47]
	v_pk_fma_f32 v[48:49], v[8:9], v[202:203], v[48:49]
	v_pk_fma_f32 v[50:51], v[6:7], v[204:205], v[50:51]
	v_pk_fma_f32 v[52:53], v[4:5], v[206:207], v[52:53]
	v_pk_fma_f32 v[46:47], v[14:15], v[192:193], v[46:47]
	v_pk_fma_f32 v[48:49], v[24:25], v[194:195], v[48:49]
	v_pk_fma_f32 v[50:51], v[44:45], v[196:197], v[50:51]
	v_pk_fma_f32 v[52:53], v[16:17], v[198:199], v[52:53]
	v_pk_mul_f32 v[46:47], v[46:47], v[244:245]
	v_pk_mul_f32 v[48:49], v[48:49], v[246:247]
	v_pk_mul_f32 v[50:51], v[50:51], v[248:249]
	v_pk_mul_f32 v[52:53], v[52:53], v[250:251]
	v_cvt_pk_bf16_f32 v34, v46, v48
	v_cvt_pk_bf16_f32 v35, v47, v49
	v_cvt_pk_bf16_f32 v36, v50, v52
	v_cvt_pk_bf16_f32 v37, v51, v53
	global_store_dwordx4 v55, v[34:37], s[90:91] offset:2048 sc1
	s_nop 1
	s_waitcnt vmcnt(28)
	v_lshlrev_b32_e32 v200, 16, v80
	v_lshlrev_b32_e32 v201, 16, v81
	v_and_b32_e32 v202, s33, v80
	v_and_b32_e32 v203, s33, v81
	v_lshlrev_b32_e32 v204, 16, v82
	v_lshlrev_b32_e32 v205, 16, v83
	v_and_b32_e32 v206, s33, v82
	v_and_b32_e32 v207, s33, v83
	v_lshlrev_b32_e32 v244, 16, v84
	v_lshlrev_b32_e32 v245, 16, v85
	v_and_b32_e32 v246, s33, v84
	v_and_b32_e32 v247, s33, v85
	v_lshlrev_b32_e32 v248, 16, v86
	v_lshlrev_b32_e32 v249, 16, v87
	v_and_b32_e32 v250, s33, v86
	v_and_b32_e32 v251, s33, v87
	v_pk_mul_f32 v[46:47], v[10:11], v[192:193]
	v_pk_mul_f32 v[48:49], v[20:21], v[194:195]
	v_pk_mul_f32 v[50:51], v[42:43], v[196:197]
	v_pk_mul_f32 v[52:53], v[12:13], v[198:199]
	v_pk_fma_f32 v[46:47], v[40:41], v[236:237], v[46:47]
	v_pk_fma_f32 v[48:49], v[8:9], v[238:239], v[48:49]
	v_pk_fma_f32 v[50:51], v[6:7], v[240:241], v[50:51]
	v_pk_fma_f32 v[52:53], v[4:5], v[242:243], v[52:53]
	v_pk_fma_f32 v[46:47], v[14:15], v[200:201], v[46:47]
	v_pk_fma_f32 v[48:49], v[24:25], v[202:203], v[48:49]
	v_pk_fma_f32 v[50:51], v[44:45], v[204:205], v[50:51]
	v_pk_fma_f32 v[52:53], v[16:17], v[206:207], v[52:53]
	v_pk_mul_f32 v[46:47], v[46:47], v[244:245]
	v_pk_mul_f32 v[48:49], v[48:49], v[246:247]
	v_pk_mul_f32 v[50:51], v[50:51], v[248:249]
	v_pk_mul_f32 v[52:53], v[52:53], v[250:251]
	v_cvt_pk_bf16_f32 v60, v46, v48
	v_cvt_pk_bf16_f32 v61, v47, v49
	v_cvt_pk_bf16_f32 v62, v50, v52
	v_cvt_pk_bf16_f32 v63, v51, v53
	v_add_u32_e32 v55, 0x1000, v55
	global_store_dwordx4 v55, v[60:63], s[90:91] sc1
	s_nop 1
	s_waitcnt vmcnt(27)
	v_lshlrev_b32_e32 v236, 16, v88
	v_lshlrev_b32_e32 v237, 16, v89
	v_and_b32_e32 v238, s33, v88
	v_and_b32_e32 v239, s33, v89
	v_lshlrev_b32_e32 v240, 16, v90
	v_lshlrev_b32_e32 v241, 16, v91
	v_and_b32_e32 v242, s33, v90
	v_and_b32_e32 v243, s33, v91
	v_lshlrev_b32_e32 v244, 16, v92
	v_lshlrev_b32_e32 v245, 16, v93
	v_and_b32_e32 v246, s33, v92
	v_and_b32_e32 v247, s33, v93
	v_lshlrev_b32_e32 v248, 16, v94
	v_lshlrev_b32_e32 v249, 16, v95
	v_and_b32_e32 v250, s33, v94
	v_and_b32_e32 v251, s33, v95
	v_pk_mul_f32 v[46:47], v[10:11], v[200:201]
	v_pk_mul_f32 v[48:49], v[20:21], v[202:203]
	v_pk_mul_f32 v[50:51], v[42:43], v[204:205]
	v_pk_mul_f32 v[52:53], v[12:13], v[206:207]
	v_pk_fma_f32 v[46:47], v[40:41], v[192:193], v[46:47]
	v_pk_fma_f32 v[48:49], v[8:9], v[194:195], v[48:49]
	v_pk_fma_f32 v[50:51], v[6:7], v[196:197], v[50:51]
	v_pk_fma_f32 v[52:53], v[4:5], v[198:199], v[52:53]
	v_pk_fma_f32 v[46:47], v[14:15], v[236:237], v[46:47]
	v_pk_fma_f32 v[48:49], v[24:25], v[238:239], v[48:49]
	v_pk_fma_f32 v[50:51], v[44:45], v[240:241], v[50:51]
	v_pk_fma_f32 v[52:53], v[16:17], v[242:243], v[52:53]
	v_pk_mul_f32 v[46:47], v[46:47], v[244:245]
	v_pk_mul_f32 v[48:49], v[48:49], v[246:247]
	v_pk_mul_f32 v[50:51], v[50:51], v[248:249]
	v_pk_mul_f32 v[52:53], v[52:53], v[250:251]
	v_cvt_pk_bf16_f32 v34, v46, v48
	v_cvt_pk_bf16_f32 v35, v47, v49
	v_cvt_pk_bf16_f32 v36, v50, v52
	v_cvt_pk_bf16_f32 v37, v51, v53
	global_store_dwordx4 v55, v[34:37], s[90:91] offset:2048 sc1
	s_nop 1
	s_waitcnt vmcnt(26)
	v_lshlrev_b32_e32 v192, 16, v96
	v_lshlrev_b32_e32 v193, 16, v97
	v_and_b32_e32 v194, s33, v96
	v_and_b32_e32 v195, s33, v97
	v_lshlrev_b32_e32 v196, 16, v98
	v_lshlrev_b32_e32 v197, 16, v99
	v_and_b32_e32 v198, s33, v98
	v_and_b32_e32 v199, s33, v99
	v_lshlrev_b32_e32 v244, 16, v100
	v_lshlrev_b32_e32 v245, 16, v101
	v_and_b32_e32 v246, s33, v100
	v_and_b32_e32 v247, s33, v101
	v_lshlrev_b32_e32 v248, 16, v102
	v_lshlrev_b32_e32 v249, 16, v103
	v_and_b32_e32 v250, s33, v102
	v_and_b32_e32 v251, s33, v103
	v_pk_mul_f32 v[46:47], v[10:11], v[236:237]
	v_pk_mul_f32 v[48:49], v[20:21], v[238:239]
	v_pk_mul_f32 v[50:51], v[42:43], v[240:241]
	v_pk_mul_f32 v[52:53], v[12:13], v[242:243]
	v_pk_fma_f32 v[46:47], v[40:41], v[200:201], v[46:47]
	v_pk_fma_f32 v[48:49], v[8:9], v[202:203], v[48:49]
	v_pk_fma_f32 v[50:51], v[6:7], v[204:205], v[50:51]
	v_pk_fma_f32 v[52:53], v[4:5], v[206:207], v[52:53]
	v_pk_fma_f32 v[46:47], v[14:15], v[192:193], v[46:47]
	v_pk_fma_f32 v[48:49], v[24:25], v[194:195], v[48:49]
	v_pk_fma_f32 v[50:51], v[44:45], v[196:197], v[50:51]
	v_pk_fma_f32 v[52:53], v[16:17], v[198:199], v[52:53]
	v_pk_mul_f32 v[46:47], v[46:47], v[244:245]
	v_pk_mul_f32 v[48:49], v[48:49], v[246:247]
	v_pk_mul_f32 v[50:51], v[50:51], v[248:249]
	v_pk_mul_f32 v[52:53], v[52:53], v[250:251]
	v_cvt_pk_bf16_f32 v60, v46, v48
	v_cvt_pk_bf16_f32 v61, v47, v49
	v_cvt_pk_bf16_f32 v62, v50, v52
	v_cvt_pk_bf16_f32 v63, v51, v53
	v_add_u32_e32 v55, 0x1000, v55
	global_store_dwordx4 v55, v[60:63], s[90:91] sc1
	s_nop 1
	s_waitcnt vmcnt(25)
	v_lshlrev_b32_e32 v200, 16, v104
	v_lshlrev_b32_e32 v201, 16, v105
	v_and_b32_e32 v202, s33, v104
	v_and_b32_e32 v203, s33, v105
	v_lshlrev_b32_e32 v204, 16, v106
	v_lshlrev_b32_e32 v205, 16, v107
	v_and_b32_e32 v206, s33, v106
	v_and_b32_e32 v207, s33, v107
	v_lshlrev_b32_e32 v244, 16, v108
	v_lshlrev_b32_e32 v245, 16, v109
	v_and_b32_e32 v246, s33, v108
	v_and_b32_e32 v247, s33, v109
	v_lshlrev_b32_e32 v248, 16, v110
	v_lshlrev_b32_e32 v249, 16, v111
	v_and_b32_e32 v250, s33, v110
	v_and_b32_e32 v251, s33, v111
	v_pk_mul_f32 v[46:47], v[10:11], v[192:193]
	v_pk_mul_f32 v[48:49], v[20:21], v[194:195]
	v_pk_mul_f32 v[50:51], v[42:43], v[196:197]
	v_pk_mul_f32 v[52:53], v[12:13], v[198:199]
	v_pk_fma_f32 v[46:47], v[40:41], v[236:237], v[46:47]
	v_pk_fma_f32 v[48:49], v[8:9], v[238:239], v[48:49]
	v_pk_fma_f32 v[50:51], v[6:7], v[240:241], v[50:51]
	v_pk_fma_f32 v[52:53], v[4:5], v[242:243], v[52:53]
	v_pk_fma_f32 v[46:47], v[14:15], v[200:201], v[46:47]
	v_pk_fma_f32 v[48:49], v[24:25], v[202:203], v[48:49]
	v_pk_fma_f32 v[50:51], v[44:45], v[204:205], v[50:51]
	v_pk_fma_f32 v[52:53], v[16:17], v[206:207], v[52:53]
	v_pk_mul_f32 v[46:47], v[46:47], v[244:245]
	v_pk_mul_f32 v[48:49], v[48:49], v[246:247]
	v_pk_mul_f32 v[50:51], v[50:51], v[248:249]
	v_pk_mul_f32 v[52:53], v[52:53], v[250:251]
	v_cvt_pk_bf16_f32 v34, v46, v48
	v_cvt_pk_bf16_f32 v35, v47, v49
	v_cvt_pk_bf16_f32 v36, v50, v52
	v_cvt_pk_bf16_f32 v37, v51, v53
	global_store_dwordx4 v55, v[34:37], s[90:91] offset:2048 sc1
	s_nop 1
	s_waitcnt vmcnt(24)
	v_lshlrev_b32_e32 v236, 16, v112
	v_lshlrev_b32_e32 v237, 16, v113
	v_and_b32_e32 v238, s33, v112
	v_and_b32_e32 v239, s33, v113
	v_lshlrev_b32_e32 v240, 16, v114
	v_lshlrev_b32_e32 v241, 16, v115
	v_and_b32_e32 v242, s33, v114
	v_and_b32_e32 v243, s33, v115
	v_lshlrev_b32_e32 v244, 16, v116
	v_lshlrev_b32_e32 v245, 16, v117
	v_and_b32_e32 v246, s33, v116
	v_and_b32_e32 v247, s33, v117
	v_lshlrev_b32_e32 v248, 16, v118
	v_lshlrev_b32_e32 v249, 16, v119
	v_and_b32_e32 v250, s33, v118
	v_and_b32_e32 v251, s33, v119
	v_pk_mul_f32 v[46:47], v[10:11], v[200:201]
	v_pk_mul_f32 v[48:49], v[20:21], v[202:203]
	v_pk_mul_f32 v[50:51], v[42:43], v[204:205]
	v_pk_mul_f32 v[52:53], v[12:13], v[206:207]
	v_pk_fma_f32 v[46:47], v[40:41], v[192:193], v[46:47]
	v_pk_fma_f32 v[48:49], v[8:9], v[194:195], v[48:49]
	v_pk_fma_f32 v[50:51], v[6:7], v[196:197], v[50:51]
	v_pk_fma_f32 v[52:53], v[4:5], v[198:199], v[52:53]
	v_pk_fma_f32 v[46:47], v[14:15], v[236:237], v[46:47]
	v_pk_fma_f32 v[48:49], v[24:25], v[238:239], v[48:49]
	v_pk_fma_f32 v[50:51], v[44:45], v[240:241], v[50:51]
	v_pk_fma_f32 v[52:53], v[16:17], v[242:243], v[52:53]
	v_pk_mul_f32 v[46:47], v[46:47], v[244:245]
	v_pk_mul_f32 v[48:49], v[48:49], v[246:247]
	v_pk_mul_f32 v[50:51], v[50:51], v[248:249]
	v_pk_mul_f32 v[52:53], v[52:53], v[250:251]
	v_cvt_pk_bf16_f32 v60, v46, v48
	v_cvt_pk_bf16_f32 v61, v47, v49
	v_cvt_pk_bf16_f32 v62, v50, v52
	v_cvt_pk_bf16_f32 v63, v51, v53
	v_add_u32_e32 v55, 0x1000, v55
	global_store_dwordx4 v55, v[60:63], s[90:91] sc1
	s_nop 1
	s_waitcnt vmcnt(23)
	v_lshlrev_b32_e32 v192, 16, v120
	v_lshlrev_b32_e32 v193, 16, v121
	v_and_b32_e32 v194, s33, v120
	v_and_b32_e32 v195, s33, v121
	v_lshlrev_b32_e32 v196, 16, v122
	v_lshlrev_b32_e32 v197, 16, v123
	v_and_b32_e32 v198, s33, v122
	v_and_b32_e32 v199, s33, v123
	v_lshlrev_b32_e32 v244, 16, v124
	v_lshlrev_b32_e32 v245, 16, v125
	v_and_b32_e32 v246, s33, v124
	v_and_b32_e32 v247, s33, v125
	v_lshlrev_b32_e32 v248, 16, v126
	v_lshlrev_b32_e32 v249, 16, v127
	v_and_b32_e32 v250, s33, v126
	v_and_b32_e32 v251, s33, v127
	v_pk_mul_f32 v[46:47], v[10:11], v[236:237]
	v_pk_mul_f32 v[48:49], v[20:21], v[238:239]
	v_pk_mul_f32 v[50:51], v[42:43], v[240:241]
	v_pk_mul_f32 v[52:53], v[12:13], v[242:243]
	v_pk_fma_f32 v[46:47], v[40:41], v[200:201], v[46:47]
	v_pk_fma_f32 v[48:49], v[8:9], v[202:203], v[48:49]
	v_pk_fma_f32 v[50:51], v[6:7], v[204:205], v[50:51]
	v_pk_fma_f32 v[52:53], v[4:5], v[206:207], v[52:53]
	v_pk_fma_f32 v[46:47], v[14:15], v[192:193], v[46:47]
	v_pk_fma_f32 v[48:49], v[24:25], v[194:195], v[48:49]
	v_pk_fma_f32 v[50:51], v[44:45], v[196:197], v[50:51]
	v_pk_fma_f32 v[52:53], v[16:17], v[198:199], v[52:53]
	v_pk_mul_f32 v[46:47], v[46:47], v[244:245]
	v_pk_mul_f32 v[48:49], v[48:49], v[246:247]
	v_pk_mul_f32 v[50:51], v[50:51], v[248:249]
	v_pk_mul_f32 v[52:53], v[52:53], v[250:251]
	v_cvt_pk_bf16_f32 v34, v46, v48
	v_cvt_pk_bf16_f32 v35, v47, v49
	v_cvt_pk_bf16_f32 v36, v50, v52
	v_cvt_pk_bf16_f32 v37, v51, v53
	global_store_dwordx4 v55, v[34:37], s[90:91] offset:2048 sc1
	s_nop 1
	s_waitcnt vmcnt(22)
	v_lshlrev_b32_e32 v200, 16, v128
	v_lshlrev_b32_e32 v201, 16, v129
	v_and_b32_e32 v202, s33, v128
	v_and_b32_e32 v203, s33, v129
	v_lshlrev_b32_e32 v204, 16, v130
	v_lshlrev_b32_e32 v205, 16, v131
	v_and_b32_e32 v206, s33, v130
	v_and_b32_e32 v207, s33, v131
	v_lshlrev_b32_e32 v244, 16, v132
	v_lshlrev_b32_e32 v245, 16, v133
	v_and_b32_e32 v246, s33, v132
	v_and_b32_e32 v247, s33, v133
	v_lshlrev_b32_e32 v248, 16, v134
	v_lshlrev_b32_e32 v249, 16, v135
	v_and_b32_e32 v250, s33, v134
	v_and_b32_e32 v251, s33, v135
	v_pk_mul_f32 v[46:47], v[10:11], v[192:193]
	v_pk_mul_f32 v[48:49], v[20:21], v[194:195]
	v_pk_mul_f32 v[50:51], v[42:43], v[196:197]
	v_pk_mul_f32 v[52:53], v[12:13], v[198:199]
	v_pk_fma_f32 v[46:47], v[40:41], v[236:237], v[46:47]
	v_pk_fma_f32 v[48:49], v[8:9], v[238:239], v[48:49]
	v_pk_fma_f32 v[50:51], v[6:7], v[240:241], v[50:51]
	v_pk_fma_f32 v[52:53], v[4:5], v[242:243], v[52:53]
	v_pk_fma_f32 v[46:47], v[14:15], v[200:201], v[46:47]
	v_pk_fma_f32 v[48:49], v[24:25], v[202:203], v[48:49]
	v_pk_fma_f32 v[50:51], v[44:45], v[204:205], v[50:51]
	v_pk_fma_f32 v[52:53], v[16:17], v[206:207], v[52:53]
	v_pk_mul_f32 v[46:47], v[46:47], v[244:245]
	v_pk_mul_f32 v[48:49], v[48:49], v[246:247]
	v_pk_mul_f32 v[50:51], v[50:51], v[248:249]
	v_pk_mul_f32 v[52:53], v[52:53], v[250:251]
	v_cvt_pk_bf16_f32 v60, v46, v48
	v_cvt_pk_bf16_f32 v61, v47, v49
	v_cvt_pk_bf16_f32 v62, v50, v52
	v_cvt_pk_bf16_f32 v63, v51, v53
	v_add_u32_e32 v55, 0x1000, v55
	global_store_dwordx4 v55, v[60:63], s[90:91] sc1
	s_nop 1
	s_waitcnt vmcnt(21)
	v_lshlrev_b32_e32 v236, 16, v136
	v_lshlrev_b32_e32 v237, 16, v137
	v_and_b32_e32 v238, s33, v136
	v_and_b32_e32 v239, s33, v137
	v_lshlrev_b32_e32 v240, 16, v138
	v_lshlrev_b32_e32 v241, 16, v139
	v_and_b32_e32 v242, s33, v138
	v_and_b32_e32 v243, s33, v139
	v_lshlrev_b32_e32 v244, 16, v140
	v_lshlrev_b32_e32 v245, 16, v141
	v_and_b32_e32 v246, s33, v140
	v_and_b32_e32 v247, s33, v141
	v_lshlrev_b32_e32 v248, 16, v142
	v_lshlrev_b32_e32 v249, 16, v143
	v_and_b32_e32 v250, s33, v142
	v_and_b32_e32 v251, s33, v143
	v_pk_mul_f32 v[46:47], v[10:11], v[200:201]
	v_pk_mul_f32 v[48:49], v[20:21], v[202:203]
	v_pk_mul_f32 v[50:51], v[42:43], v[204:205]
	v_pk_mul_f32 v[52:53], v[12:13], v[206:207]
	v_pk_fma_f32 v[46:47], v[40:41], v[192:193], v[46:47]
	v_pk_fma_f32 v[48:49], v[8:9], v[194:195], v[48:49]
	v_pk_fma_f32 v[50:51], v[6:7], v[196:197], v[50:51]
	v_pk_fma_f32 v[52:53], v[4:5], v[198:199], v[52:53]
	v_pk_fma_f32 v[46:47], v[14:15], v[236:237], v[46:47]
	v_pk_fma_f32 v[48:49], v[24:25], v[238:239], v[48:49]
	v_pk_fma_f32 v[50:51], v[44:45], v[240:241], v[50:51]
	v_pk_fma_f32 v[52:53], v[16:17], v[242:243], v[52:53]
	v_pk_mul_f32 v[46:47], v[46:47], v[244:245]
	v_pk_mul_f32 v[48:49], v[48:49], v[246:247]
	v_pk_mul_f32 v[50:51], v[50:51], v[248:249]
	v_pk_mul_f32 v[52:53], v[52:53], v[250:251]
	v_cvt_pk_bf16_f32 v34, v46, v48
	v_cvt_pk_bf16_f32 v35, v47, v49
	v_cvt_pk_bf16_f32 v36, v50, v52
	v_cvt_pk_bf16_f32 v37, v51, v53
	global_store_dwordx4 v55, v[34:37], s[90:91] offset:2048 sc1
	s_nop 1
	s_waitcnt vmcnt(20)
	v_lshlrev_b32_e32 v192, 16, v144
	v_lshlrev_b32_e32 v193, 16, v145
	v_and_b32_e32 v194, s33, v144
	v_and_b32_e32 v195, s33, v145
	v_lshlrev_b32_e32 v196, 16, v146
	v_lshlrev_b32_e32 v197, 16, v147
	v_and_b32_e32 v198, s33, v146
	v_and_b32_e32 v199, s33, v147
	v_lshlrev_b32_e32 v244, 16, v148
	v_lshlrev_b32_e32 v245, 16, v149
	v_and_b32_e32 v246, s33, v148
	v_and_b32_e32 v247, s33, v149
	v_lshlrev_b32_e32 v248, 16, v150
	v_lshlrev_b32_e32 v249, 16, v151
	v_and_b32_e32 v250, s33, v150
	v_and_b32_e32 v251, s33, v151
	v_pk_mul_f32 v[46:47], v[10:11], v[236:237]
	v_pk_mul_f32 v[48:49], v[20:21], v[238:239]
	v_pk_mul_f32 v[50:51], v[42:43], v[240:241]
	v_pk_mul_f32 v[52:53], v[12:13], v[242:243]
	v_pk_fma_f32 v[46:47], v[40:41], v[200:201], v[46:47]
	v_pk_fma_f32 v[48:49], v[8:9], v[202:203], v[48:49]
	v_pk_fma_f32 v[50:51], v[6:7], v[204:205], v[50:51]
	v_pk_fma_f32 v[52:53], v[4:5], v[206:207], v[52:53]
	v_pk_fma_f32 v[46:47], v[14:15], v[192:193], v[46:47]
	v_pk_fma_f32 v[48:49], v[24:25], v[194:195], v[48:49]
	v_pk_fma_f32 v[50:51], v[44:45], v[196:197], v[50:51]
	v_pk_fma_f32 v[52:53], v[16:17], v[198:199], v[52:53]
	v_pk_mul_f32 v[46:47], v[46:47], v[244:245]
	v_pk_mul_f32 v[48:49], v[48:49], v[246:247]
	v_pk_mul_f32 v[50:51], v[50:51], v[248:249]
	v_pk_mul_f32 v[52:53], v[52:53], v[250:251]
	v_cvt_pk_bf16_f32 v60, v46, v48
	v_cvt_pk_bf16_f32 v61, v47, v49
	v_cvt_pk_bf16_f32 v62, v50, v52
	v_cvt_pk_bf16_f32 v63, v51, v53
	v_add_u32_e32 v55, 0x1000, v55
	global_store_dwordx4 v55, v[60:63], s[90:91] sc1
	s_nop 1
	s_waitcnt vmcnt(19)
	v_lshlrev_b32_e32 v200, 16, v152
	v_lshlrev_b32_e32 v201, 16, v153
	v_and_b32_e32 v202, s33, v152
	v_and_b32_e32 v203, s33, v153
	v_lshlrev_b32_e32 v204, 16, v154
	v_lshlrev_b32_e32 v205, 16, v155
	v_and_b32_e32 v206, s33, v154
	v_and_b32_e32 v207, s33, v155
	v_lshlrev_b32_e32 v244, 16, v156
	v_lshlrev_b32_e32 v245, 16, v157
	v_and_b32_e32 v246, s33, v156
	v_and_b32_e32 v247, s33, v157
	v_lshlrev_b32_e32 v248, 16, v158
	v_lshlrev_b32_e32 v249, 16, v159
	v_and_b32_e32 v250, s33, v158
	v_and_b32_e32 v251, s33, v159
	v_pk_mul_f32 v[46:47], v[10:11], v[192:193]
	v_pk_mul_f32 v[48:49], v[20:21], v[194:195]
	v_pk_mul_f32 v[50:51], v[42:43], v[196:197]
	v_pk_mul_f32 v[52:53], v[12:13], v[198:199]
	v_pk_fma_f32 v[46:47], v[40:41], v[236:237], v[46:47]
	v_pk_fma_f32 v[48:49], v[8:9], v[238:239], v[48:49]
	v_pk_fma_f32 v[50:51], v[6:7], v[240:241], v[50:51]
	v_pk_fma_f32 v[52:53], v[4:5], v[242:243], v[52:53]
	v_pk_fma_f32 v[46:47], v[14:15], v[200:201], v[46:47]
	v_pk_fma_f32 v[48:49], v[24:25], v[202:203], v[48:49]
	v_pk_fma_f32 v[50:51], v[44:45], v[204:205], v[50:51]
	v_pk_fma_f32 v[52:53], v[16:17], v[206:207], v[52:53]
	v_pk_mul_f32 v[46:47], v[46:47], v[244:245]
	v_pk_mul_f32 v[48:49], v[48:49], v[246:247]
	v_pk_mul_f32 v[50:51], v[50:51], v[248:249]
	v_pk_mul_f32 v[52:53], v[52:53], v[250:251]
	v_cvt_pk_bf16_f32 v34, v46, v48
	v_cvt_pk_bf16_f32 v35, v47, v49
	v_cvt_pk_bf16_f32 v36, v50, v52
	v_cvt_pk_bf16_f32 v37, v51, v53
	global_store_dwordx4 v55, v[34:37], s[90:91] offset:2048 sc1
	s_nop 1
	s_waitcnt vmcnt(18)
	v_lshlrev_b32_e32 v236, 16, v160
	v_lshlrev_b32_e32 v237, 16, v161
	v_and_b32_e32 v238, s33, v160
	v_and_b32_e32 v239, s33, v161
	v_lshlrev_b32_e32 v240, 16, v162
	v_lshlrev_b32_e32 v241, 16, v163
	v_and_b32_e32 v242, s33, v162
	v_and_b32_e32 v243, s33, v163
	v_lshlrev_b32_e32 v244, 16, v164
	v_lshlrev_b32_e32 v245, 16, v165
	v_and_b32_e32 v246, s33, v164
	v_and_b32_e32 v247, s33, v165
	v_lshlrev_b32_e32 v248, 16, v166
	v_lshlrev_b32_e32 v249, 16, v167
	v_and_b32_e32 v250, s33, v166
	v_and_b32_e32 v251, s33, v167
	v_pk_mul_f32 v[46:47], v[10:11], v[200:201]
	v_pk_mul_f32 v[48:49], v[20:21], v[202:203]
	v_pk_mul_f32 v[50:51], v[42:43], v[204:205]
	v_pk_mul_f32 v[52:53], v[12:13], v[206:207]
	v_pk_fma_f32 v[46:47], v[40:41], v[192:193], v[46:47]
	v_pk_fma_f32 v[48:49], v[8:9], v[194:195], v[48:49]
	v_pk_fma_f32 v[50:51], v[6:7], v[196:197], v[50:51]
	v_pk_fma_f32 v[52:53], v[4:5], v[198:199], v[52:53]
	v_pk_fma_f32 v[46:47], v[14:15], v[236:237], v[46:47]
	v_pk_fma_f32 v[48:49], v[24:25], v[238:239], v[48:49]
	v_pk_fma_f32 v[50:51], v[44:45], v[240:241], v[50:51]
	v_pk_fma_f32 v[52:53], v[16:17], v[242:243], v[52:53]
	v_pk_mul_f32 v[46:47], v[46:47], v[244:245]
	v_pk_mul_f32 v[48:49], v[48:49], v[246:247]
	v_pk_mul_f32 v[50:51], v[50:51], v[248:249]
	v_pk_mul_f32 v[52:53], v[52:53], v[250:251]
	v_cvt_pk_bf16_f32 v60, v46, v48
	v_cvt_pk_bf16_f32 v61, v47, v49
	v_cvt_pk_bf16_f32 v62, v50, v52
	v_cvt_pk_bf16_f32 v63, v51, v53
	v_add_u32_e32 v55, 0x1000, v55
	global_store_dwordx4 v55, v[60:63], s[90:91] sc1
	s_nop 1
	s_waitcnt vmcnt(17)
	v_lshlrev_b32_e32 v192, 16, v168
	v_lshlrev_b32_e32 v193, 16, v169
	v_and_b32_e32 v194, s33, v168
	v_and_b32_e32 v195, s33, v169
	v_lshlrev_b32_e32 v196, 16, v170
	v_lshlrev_b32_e32 v197, 16, v171
	v_and_b32_e32 v198, s33, v170
	v_and_b32_e32 v199, s33, v171
	v_lshlrev_b32_e32 v244, 16, v172
	v_lshlrev_b32_e32 v245, 16, v173
	v_and_b32_e32 v246, s33, v172
	v_and_b32_e32 v247, s33, v173
	v_lshlrev_b32_e32 v248, 16, v174
	v_lshlrev_b32_e32 v249, 16, v175
	v_and_b32_e32 v250, s33, v174
	v_and_b32_e32 v251, s33, v175
	v_pk_mul_f32 v[46:47], v[10:11], v[236:237]
	v_pk_mul_f32 v[48:49], v[20:21], v[238:239]
	v_pk_mul_f32 v[50:51], v[42:43], v[240:241]
	v_pk_mul_f32 v[52:53], v[12:13], v[242:243]
	v_pk_fma_f32 v[46:47], v[40:41], v[200:201], v[46:47]
	v_pk_fma_f32 v[48:49], v[8:9], v[202:203], v[48:49]
	v_pk_fma_f32 v[50:51], v[6:7], v[204:205], v[50:51]
	v_pk_fma_f32 v[52:53], v[4:5], v[206:207], v[52:53]
	v_pk_fma_f32 v[46:47], v[14:15], v[192:193], v[46:47]
	v_pk_fma_f32 v[48:49], v[24:25], v[194:195], v[48:49]
	v_pk_fma_f32 v[50:51], v[44:45], v[196:197], v[50:51]
	v_pk_fma_f32 v[52:53], v[16:17], v[198:199], v[52:53]
	v_pk_mul_f32 v[46:47], v[46:47], v[244:245]
	v_pk_mul_f32 v[48:49], v[48:49], v[246:247]
	v_pk_mul_f32 v[50:51], v[50:51], v[248:249]
	v_pk_mul_f32 v[52:53], v[52:53], v[250:251]
	v_cvt_pk_bf16_f32 v34, v46, v48
	v_cvt_pk_bf16_f32 v35, v47, v49
	v_cvt_pk_bf16_f32 v36, v50, v52
	v_cvt_pk_bf16_f32 v37, v51, v53
	global_store_dwordx4 v55, v[34:37], s[90:91] offset:2048 sc1
	s_nop 1
	s_waitcnt vmcnt(16)
	v_lshlrev_b32_e32 v200, 16, v176
	v_lshlrev_b32_e32 v201, 16, v177
	v_and_b32_e32 v202, s33, v176
	v_and_b32_e32 v203, s33, v177
	v_lshlrev_b32_e32 v204, 16, v178
	v_lshlrev_b32_e32 v205, 16, v179
	v_and_b32_e32 v206, s33, v178
	v_and_b32_e32 v207, s33, v179
	v_lshlrev_b32_e32 v244, 16, v180
	v_lshlrev_b32_e32 v245, 16, v181
	v_and_b32_e32 v246, s33, v180
	v_and_b32_e32 v247, s33, v181
	v_lshlrev_b32_e32 v248, 16, v182
	v_lshlrev_b32_e32 v249, 16, v183
	v_and_b32_e32 v250, s33, v182
	v_and_b32_e32 v251, s33, v183
	v_pk_mul_f32 v[46:47], v[10:11], v[192:193]
	v_pk_mul_f32 v[48:49], v[20:21], v[194:195]
	v_pk_mul_f32 v[50:51], v[42:43], v[196:197]
	v_pk_mul_f32 v[52:53], v[12:13], v[198:199]
	v_pk_fma_f32 v[46:47], v[40:41], v[236:237], v[46:47]
	v_pk_fma_f32 v[48:49], v[8:9], v[238:239], v[48:49]
	v_pk_fma_f32 v[50:51], v[6:7], v[240:241], v[50:51]
	v_pk_fma_f32 v[52:53], v[4:5], v[242:243], v[52:53]
	v_pk_fma_f32 v[46:47], v[14:15], v[200:201], v[46:47]
	v_pk_fma_f32 v[48:49], v[24:25], v[202:203], v[48:49]
	v_pk_fma_f32 v[50:51], v[44:45], v[204:205], v[50:51]
	v_pk_fma_f32 v[52:53], v[16:17], v[206:207], v[52:53]
	v_pk_mul_f32 v[46:47], v[46:47], v[244:245]
	v_pk_mul_f32 v[48:49], v[48:49], v[246:247]
	v_pk_mul_f32 v[50:51], v[50:51], v[248:249]
	v_pk_mul_f32 v[52:53], v[52:53], v[250:251]
	v_cvt_pk_bf16_f32 v60, v46, v48
	v_cvt_pk_bf16_f32 v61, v47, v49
	v_cvt_pk_bf16_f32 v62, v50, v52
	v_cvt_pk_bf16_f32 v63, v51, v53
	v_add_u32_e32 v55, 0x1000, v55
	global_store_dwordx4 v55, v[60:63], s[90:91] sc1
	s_nop 1
	s_waitcnt vmcnt(15)
	v_lshlrev_b32_e32 v236, 16, v184
	v_lshlrev_b32_e32 v237, 16, v185
	v_and_b32_e32 v238, s33, v184
	v_and_b32_e32 v239, s33, v185
	v_lshlrev_b32_e32 v240, 16, v186
	v_lshlrev_b32_e32 v241, 16, v187
	v_and_b32_e32 v242, s33, v186
	v_and_b32_e32 v243, s33, v187
	v_lshlrev_b32_e32 v244, 16, v188
	v_lshlrev_b32_e32 v245, 16, v189
	v_and_b32_e32 v246, s33, v188
	v_and_b32_e32 v247, s33, v189
	v_lshlrev_b32_e32 v248, 16, v190
	v_lshlrev_b32_e32 v249, 16, v191
	v_and_b32_e32 v250, s33, v190
	v_and_b32_e32 v251, s33, v191
	v_pk_mul_f32 v[46:47], v[10:11], v[200:201]
	v_pk_mul_f32 v[48:49], v[20:21], v[202:203]
	v_pk_mul_f32 v[50:51], v[42:43], v[204:205]
	v_pk_mul_f32 v[52:53], v[12:13], v[206:207]
	v_pk_fma_f32 v[46:47], v[40:41], v[192:193], v[46:47]
	v_pk_fma_f32 v[48:49], v[8:9], v[194:195], v[48:49]
	v_pk_fma_f32 v[50:51], v[6:7], v[196:197], v[50:51]
	v_pk_fma_f32 v[52:53], v[4:5], v[198:199], v[52:53]
	v_pk_fma_f32 v[46:47], v[14:15], v[236:237], v[46:47]
	v_pk_fma_f32 v[48:49], v[24:25], v[238:239], v[48:49]
	v_pk_fma_f32 v[50:51], v[44:45], v[240:241], v[50:51]
	v_pk_fma_f32 v[52:53], v[16:17], v[242:243], v[52:53]
	v_pk_mul_f32 v[46:47], v[46:47], v[244:245]
	v_pk_mul_f32 v[48:49], v[48:49], v[246:247]
	v_pk_mul_f32 v[50:51], v[50:51], v[248:249]
	v_pk_mul_f32 v[52:53], v[52:53], v[250:251]
	v_cvt_pk_bf16_f32 v34, v46, v48
	v_cvt_pk_bf16_f32 v35, v47, v49
	v_cvt_pk_bf16_f32 v36, v50, v52
	v_cvt_pk_bf16_f32 v37, v51, v53
	global_store_dwordx4 v55, v[34:37], s[90:91] offset:2048 sc1
	s_nop 1
	s_add_i32 s11, s11, s98
	s_cmpk_gt_i32 s11, 0xff
	v_add_u32_e32 v57, s10, v57
	s_cbranch_scc0 .LBB0_60

.LBB0_382:
	s_waitcnt vmcnt(0)
	v_lshl_or_b32 v144, s29, 7, v156
	v_lshl_add_u32 v164, s28, 8, v1
	v_ashrrev_i32_e32 v145, 31, v144
	v_mov_b64_e32 v[142:143], s[82:83]
	s_movk_i32 s21, 0x1600
	v_mad_i64_i32 v[146:147], s[28:29], v164, s21, v[142:143]
	v_lshlrev_b64 v[144:145], 1, v[144:145]
	v_lshl_add_u64 v[146:147], v[146:147], 0, v[144:145]
	s_andn2_b64 vcc, exec, s[6:7]
	v_cvt_f32_u32_e32 v166, v166
	v_fmamk_f32 v170, v166, 0x34800000, v228
	v_rsq_f32_e32 v166, v170
	v_pk_mul_f32 v[122:123], v[126:127], v[122:123]
	v_pk_mul_f32 v[124:125], v[128:129], v[124:125]
	v_pk_mul_f32 v[114:115], v[118:119], v[114:115]
	v_pk_mul_f32 v[116:117], v[120:121], v[116:117]
	v_mul_f32_e32 v172, 0xbfb8aa3b, v166
	v_pk_mul_f32 v[126:127], v[126:127], v[172:173] op_sel_hi:[1,0]
	v_pk_mul_f32 v[128:129], v[128:129], v[172:173] op_sel_hi:[1,0]
	v_pk_mul_f32 v[118:119], v[118:119], v[172:173] op_sel_hi:[1,0]
	v_pk_mul_f32 v[120:121], v[120:121], v[172:173] op_sel_hi:[1,0]
	v_exp_f32_e32 v126, v126
	v_exp_f32_e32 v127, v127
	v_exp_f32_e32 v128, v128
	v_exp_f32_e32 v129, v129
	v_exp_f32_e32 v118, v118
	v_exp_f32_e32 v119, v119
	v_exp_f32_e32 v120, v120
	v_exp_f32_e32 v121, v121
	v_pk_fma_f32 v[126:127], v[126:127], v[170:171], v[170:171] op_sel_hi:[1,0,0]
	v_pk_fma_f32 v[128:129], v[128:129], v[170:171], v[170:171] op_sel_hi:[1,0,0]
	v_pk_fma_f32 v[118:119], v[118:119], v[170:171], v[170:171] op_sel_hi:[1,0,0]
	v_pk_fma_f32 v[120:121], v[120:121], v[170:171], v[170:171] op_sel_hi:[1,0,0]
	v_rcp_f32_e32 v126, v126
	v_rcp_f32_e32 v127, v127
	v_rcp_f32_e32 v128, v128
	v_rcp_f32_e32 v129, v129
	v_rcp_f32_e32 v118, v118
	v_rcp_f32_e32 v119, v119
	v_rcp_f32_e32 v120, v120
	v_rcp_f32_e32 v121, v121
	v_pk_mul_f32 v[122:123], v[122:123], v[126:127]
	v_pk_mul_f32 v[124:125], v[124:125], v[128:129]
	v_pk_mul_f32 v[118:119], v[114:115], v[118:119]
	v_pk_mul_f32 v[120:121], v[116:117], v[120:121]
	v_cvt_pk_bf16_f32 v114, v122, v123
	v_cvt_pk_bf16_f32 v115, v124, v125
	v_cvt_pk_bf16_f32 v116, v118, v119
	v_cvt_pk_bf16_f32 v117, v120, v121
	global_store_dwordx4 v[146:147], v[114:117], off sc1
	s_nop 1
	v_cvt_f32_u32_e32 v165, v165
	v_fmamk_f32 v170, v165, 0x34800000, v228
	v_rsq_f32_e32 v165, v170
	v_pk_mul_f32 v[106:107], v[110:111], v[106:107]
	v_pk_mul_f32 v[108:109], v[112:113], v[108:109]
	v_pk_mul_f32 v[98:99], v[102:103], v[98:99]
	v_pk_mul_f32 v[100:101], v[104:105], v[100:101]
	v_mul_f32_e32 v172, 0xbfb8aa3b, v165
	v_pk_mul_f32 v[110:111], v[110:111], v[172:173] op_sel_hi:[1,0]
	v_pk_mul_f32 v[112:113], v[112:113], v[172:173] op_sel_hi:[1,0]
	v_pk_mul_f32 v[102:103], v[102:103], v[172:173] op_sel_hi:[1,0]
	v_pk_mul_f32 v[104:105], v[104:105], v[172:173] op_sel_hi:[1,0]
	v_exp_f32_e32 v110, v110
	v_exp_f32_e32 v111, v111
	v_exp_f32_e32 v112, v112
	v_exp_f32_e32 v113, v113
	v_exp_f32_e32 v102, v102
	v_exp_f32_e32 v103, v103
	v_exp_f32_e32 v104, v104
	v_exp_f32_e32 v105, v105
	v_or_b32_e32 v114, 16, v164
	v_mad_i64_i32 v[114:115], s[28:29], v114, s21, v[142:143]
	v_lshl_add_u64 v[114:115], v[114:115], 0, v[144:145]
	v_pk_fma_f32 v[110:111], v[110:111], v[170:171], v[170:171] op_sel_hi:[1,0,0]
	v_pk_fma_f32 v[112:113], v[112:113], v[170:171], v[170:171] op_sel_hi:[1,0,0]
	v_pk_fma_f32 v[102:103], v[102:103], v[170:171], v[170:171] op_sel_hi:[1,0,0]
	v_pk_fma_f32 v[104:105], v[104:105], v[170:171], v[170:171] op_sel_hi:[1,0,0]
	v_rcp_f32_e32 v110, v110
	v_rcp_f32_e32 v111, v111
	v_rcp_f32_e32 v112, v112
	v_rcp_f32_e32 v113, v113
	v_rcp_f32_e32 v102, v102
	v_rcp_f32_e32 v103, v103
	v_rcp_f32_e32 v104, v104
	v_rcp_f32_e32 v105, v105
	v_pk_mul_f32 v[106:107], v[106:107], v[110:111]
	v_pk_mul_f32 v[108:109], v[108:109], v[112:113]
	v_pk_mul_f32 v[102:103], v[98:99], v[102:103]
	v_pk_mul_f32 v[104:105], v[100:101], v[104:105]
	v_cvt_pk_bf16_f32 v98, v106, v107
	v_cvt_pk_bf16_f32 v99, v108, v109
	v_cvt_pk_bf16_f32 v100, v102, v103
	v_cvt_pk_bf16_f32 v101, v104, v105
	global_store_dwordx4 v[114:115], v[98:101], off sc1
	s_nop 1
	v_cvt_f32_u32_e32 v163, v163
	v_fmamk_f32 v170, v163, 0x34800000, v228
	v_rsq_f32_e32 v163, v170
	v_pk_mul_f32 v[90:91], v[94:95], v[90:91]
	v_pk_mul_f32 v[92:93], v[96:97], v[92:93]
	v_pk_mul_f32 v[82:83], v[86:87], v[82:83]
	v_pk_mul_f32 v[84:85], v[88:89], v[84:85]
	v_mul_f32_e32 v172, 0xbfb8aa3b, v163
	v_pk_mul_f32 v[94:95], v[94:95], v[172:173] op_sel_hi:[1,0]
	v_pk_mul_f32 v[96:97], v[96:97], v[172:173] op_sel_hi:[1,0]
	v_pk_mul_f32 v[86:87], v[86:87], v[172:173] op_sel_hi:[1,0]
	v_pk_mul_f32 v[88:89], v[88:89], v[172:173] op_sel_hi:[1,0]
	v_exp_f32_e32 v94, v94
	v_exp_f32_e32 v95, v95
	v_exp_f32_e32 v96, v96
	v_exp_f32_e32 v97, v97
	v_exp_f32_e32 v86, v86
	v_exp_f32_e32 v87, v87
	v_exp_f32_e32 v88, v88
	v_exp_f32_e32 v89, v89
	v_or_b32_e32 v98, 32, v164
	v_mad_i64_i32 v[98:99], s[28:29], v98, s21, v[142:143]
	v_lshl_add_u64 v[98:99], v[98:99], 0, v[144:145]
	v_pk_fma_f32 v[94:95], v[94:95], v[170:171], v[170:171] op_sel_hi:[1,0,0]
	v_pk_fma_f32 v[96:97], v[96:97], v[170:171], v[170:171] op_sel_hi:[1,0,0]
	v_pk_fma_f32 v[86:87], v[86:87], v[170:171], v[170:171] op_sel_hi:[1,0,0]
	v_pk_fma_f32 v[88:89], v[88:89], v[170:171], v[170:171] op_sel_hi:[1,0,0]
	v_rcp_f32_e32 v94, v94
	v_rcp_f32_e32 v95, v95
	v_rcp_f32_e32 v96, v96
	v_rcp_f32_e32 v97, v97
	v_rcp_f32_e32 v86, v86
	v_rcp_f32_e32 v87, v87
	v_rcp_f32_e32 v88, v88
	v_rcp_f32_e32 v89, v89
	v_pk_mul_f32 v[90:91], v[90:91], v[94:95]
	v_pk_mul_f32 v[92:93], v[92:93], v[96:97]
	v_pk_mul_f32 v[86:87], v[82:83], v[86:87]
	v_pk_mul_f32 v[88:89], v[84:85], v[88:89]
	v_cvt_pk_bf16_f32 v82, v90, v91
	v_cvt_pk_bf16_f32 v83, v92, v93
	v_cvt_pk_bf16_f32 v84, v86, v87
	v_cvt_pk_bf16_f32 v85, v88, v89
	global_store_dwordx4 v[98:99], v[82:85], off sc1
	s_nop 1
	v_cvt_f32_u32_e32 v162, v162
	v_fmamk_f32 v170, v162, 0x34800000, v228
	v_rsq_f32_e32 v162, v170
	v_pk_mul_f32 v[74:75], v[78:79], v[74:75]
	v_pk_mul_f32 v[76:77], v[80:81], v[76:77]
	v_pk_mul_f32 v[66:67], v[70:71], v[66:67]
	v_pk_mul_f32 v[68:69], v[72:73], v[68:69]
	v_mul_f32_e32 v172, 0xbfb8aa3b, v162
	v_pk_mul_f32 v[78:79], v[78:79], v[172:173] op_sel_hi:[1,0]
	v_pk_mul_f32 v[80:81], v[80:81], v[172:173] op_sel_hi:[1,0]
	v_pk_mul_f32 v[70:71], v[70:71], v[172:173] op_sel_hi:[1,0]
	v_pk_mul_f32 v[72:73], v[72:73], v[172:173] op_sel_hi:[1,0]
	v_exp_f32_e32 v78, v78
	v_exp_f32_e32 v79, v79
	v_exp_f32_e32 v80, v80
	v_exp_f32_e32 v81, v81
	v_exp_f32_e32 v70, v70
	v_exp_f32_e32 v71, v71
	v_exp_f32_e32 v72, v72
	v_exp_f32_e32 v73, v73
	v_or_b32_e32 v82, 48, v164
	v_mad_i64_i32 v[82:83], s[28:29], v82, s21, v[142:143]
	v_lshl_add_u64 v[82:83], v[82:83], 0, v[144:145]
	v_pk_fma_f32 v[78:79], v[78:79], v[170:171], v[170:171] op_sel_hi:[1,0,0]
	v_pk_fma_f32 v[80:81], v[80:81], v[170:171], v[170:171] op_sel_hi:[1,0,0]
	v_pk_fma_f32 v[70:71], v[70:71], v[170:171], v[170:171] op_sel_hi:[1,0,0]
	v_pk_fma_f32 v[72:73], v[72:73], v[170:171], v[170:171] op_sel_hi:[1,0,0]
	v_rcp_f32_e32 v78, v78
	v_rcp_f32_e32 v79, v79
	v_rcp_f32_e32 v80, v80
	v_rcp_f32_e32 v81, v81
	v_rcp_f32_e32 v70, v70
	v_rcp_f32_e32 v71, v71
	v_rcp_f32_e32 v72, v72
	v_rcp_f32_e32 v73, v73
	v_pk_mul_f32 v[74:75], v[74:75], v[78:79]
	v_pk_mul_f32 v[76:77], v[76:77], v[80:81]
	v_pk_mul_f32 v[70:71], v[66:67], v[70:71]
	v_pk_mul_f32 v[72:73], v[68:69], v[72:73]
	v_cvt_pk_bf16_f32 v66, v74, v75
	v_cvt_pk_bf16_f32 v67, v76, v77
	v_cvt_pk_bf16_f32 v68, v70, v71
	v_cvt_pk_bf16_f32 v69, v72, v73
	global_store_dwordx4 v[82:83], v[66:69], off sc1
	s_nop 1
	v_cvt_f32_u32_e32 v161, v161
	v_fmamk_f32 v170, v161, 0x34800000, v228
	v_rsq_f32_e32 v161, v170
	v_pk_mul_f32 v[58:59], v[62:63], v[58:59]
	v_pk_mul_f32 v[60:61], v[64:65], v[60:61]
	v_pk_mul_f32 v[50:51], v[54:55], v[50:51]
	v_pk_mul_f32 v[52:53], v[56:57], v[52:53]
	v_mul_f32_e32 v172, 0xbfb8aa3b, v161
	v_pk_mul_f32 v[62:63], v[62:63], v[172:173] op_sel_hi:[1,0]
	v_pk_mul_f32 v[64:65], v[64:65], v[172:173] op_sel_hi:[1,0]
	v_pk_mul_f32 v[54:55], v[54:55], v[172:173] op_sel_hi:[1,0]
	v_pk_mul_f32 v[56:57], v[56:57], v[172:173] op_sel_hi:[1,0]
	v_exp_f32_e32 v62, v62
	v_exp_f32_e32 v63, v63
	v_exp_f32_e32 v64, v64
	v_exp_f32_e32 v65, v65
	v_exp_f32_e32 v54, v54
	v_exp_f32_e32 v55, v55
	v_exp_f32_e32 v56, v56
	v_exp_f32_e32 v57, v57
	v_add_u32_e32 v66, 0x80, v164
	v_mad_i64_i32 v[66:67], s[28:29], v66, s21, v[142:143]
	v_lshl_add_u64 v[66:67], v[66:67], 0, v[144:145]
	v_pk_fma_f32 v[62:63], v[62:63], v[170:171], v[170:171] op_sel_hi:[1,0,0]
	v_pk_fma_f32 v[64:65], v[64:65], v[170:171], v[170:171] op_sel_hi:[1,0,0]
	v_pk_fma_f32 v[54:55], v[54:55], v[170:171], v[170:171] op_sel_hi:[1,0,0]
	v_pk_fma_f32 v[56:57], v[56:57], v[170:171], v[170:171] op_sel_hi:[1,0,0]
	v_rcp_f32_e32 v62, v62
	v_rcp_f32_e32 v63, v63
	v_rcp_f32_e32 v64, v64
	v_rcp_f32_e32 v65, v65
	v_rcp_f32_e32 v54, v54
	v_rcp_f32_e32 v55, v55
	v_rcp_f32_e32 v56, v56
	v_rcp_f32_e32 v57, v57
	v_pk_mul_f32 v[58:59], v[58:59], v[62:63]
	v_pk_mul_f32 v[60:61], v[60:61], v[64:65]
	v_pk_mul_f32 v[54:55], v[50:51], v[54:55]
	v_pk_mul_f32 v[56:57], v[52:53], v[56:57]
	v_cvt_pk_bf16_f32 v50, v58, v59
	v_cvt_pk_bf16_f32 v51, v60, v61
	v_cvt_pk_bf16_f32 v52, v54, v55
	v_cvt_pk_bf16_f32 v53, v56, v57
	global_store_dwordx4 v[66:67], v[50:53], off sc1
	s_nop 1
	v_cvt_f32_u32_e32 v160, v160
	v_fmamk_f32 v170, v160, 0x34800000, v228
	v_rsq_f32_e32 v160, v170
	v_pk_mul_f32 v[42:43], v[46:47], v[42:43]
	v_pk_mul_f32 v[44:45], v[48:49], v[44:45]
	v_pk_mul_f32 v[34:35], v[38:39], v[34:35]
	v_pk_mul_f32 v[36:37], v[40:41], v[36:37]
	v_mul_f32_e32 v172, 0xbfb8aa3b, v160
	v_pk_mul_f32 v[46:47], v[46:47], v[172:173] op_sel_hi:[1,0]
	v_pk_mul_f32 v[48:49], v[48:49], v[172:173] op_sel_hi:[1,0]
	v_pk_mul_f32 v[38:39], v[38:39], v[172:173] op_sel_hi:[1,0]
	v_pk_mul_f32 v[40:41], v[40:41], v[172:173] op_sel_hi:[1,0]
	v_exp_f32_e32 v46, v46
	v_exp_f32_e32 v47, v47
	v_exp_f32_e32 v48, v48
	v_exp_f32_e32 v49, v49
	v_exp_f32_e32 v38, v38
	v_exp_f32_e32 v39, v39
	v_exp_f32_e32 v40, v40
	v_exp_f32_e32 v41, v41
	v_add_u32_e32 v50, 0x90, v164
	v_mad_i64_i32 v[50:51], s[28:29], v50, s21, v[142:143]
	v_lshl_add_u64 v[50:51], v[50:51], 0, v[144:145]
	v_pk_fma_f32 v[46:47], v[46:47], v[170:171], v[170:171] op_sel_hi:[1,0,0]
	v_pk_fma_f32 v[48:49], v[48:49], v[170:171], v[170:171] op_sel_hi:[1,0,0]
	v_pk_fma_f32 v[38:39], v[38:39], v[170:171], v[170:171] op_sel_hi:[1,0,0]
	v_pk_fma_f32 v[40:41], v[40:41], v[170:171], v[170:171] op_sel_hi:[1,0,0]
	v_rcp_f32_e32 v46, v46
	v_rcp_f32_e32 v47, v47
	v_rcp_f32_e32 v48, v48
	v_rcp_f32_e32 v49, v49
	v_rcp_f32_e32 v38, v38
	v_rcp_f32_e32 v39, v39
	v_rcp_f32_e32 v40, v40
	v_rcp_f32_e32 v41, v41
	v_pk_mul_f32 v[42:43], v[42:43], v[46:47]
	v_pk_mul_f32 v[44:45], v[44:45], v[48:49]
	v_pk_mul_f32 v[38:39], v[34:35], v[38:39]
	v_pk_mul_f32 v[40:41], v[36:37], v[40:41]
	v_cvt_pk_bf16_f32 v34, v42, v43
	v_cvt_pk_bf16_f32 v35, v44, v45
	v_cvt_pk_bf16_f32 v36, v38, v39
	v_cvt_pk_bf16_f32 v37, v40, v41
	global_store_dwordx4 v[50:51], v[34:37], off sc1
	s_nop 1
	v_cvt_f32_u32_e32 v159, v159
	v_fmamk_f32 v170, v159, 0x34800000, v228
	v_rsq_f32_e32 v159, v170
	v_pk_mul_f32 v[26:27], v[30:31], v[26:27]
	v_pk_mul_f32 v[28:29], v[32:33], v[28:29]
	v_pk_mul_f32 v[18:19], v[22:23], v[18:19]
	v_pk_mul_f32 v[20:21], v[24:25], v[20:21]
	v_mul_f32_e32 v172, 0xbfb8aa3b, v159
	v_pk_mul_f32 v[30:31], v[30:31], v[172:173] op_sel_hi:[1,0]
	v_pk_mul_f32 v[32:33], v[32:33], v[172:173] op_sel_hi:[1,0]
	v_pk_mul_f32 v[22:23], v[22:23], v[172:173] op_sel_hi:[1,0]
	v_pk_mul_f32 v[24:25], v[24:25], v[172:173] op_sel_hi:[1,0]
	v_exp_f32_e32 v30, v30
	v_exp_f32_e32 v31, v31
	v_exp_f32_e32 v32, v32
	v_exp_f32_e32 v33, v33
	v_exp_f32_e32 v22, v22
	v_exp_f32_e32 v23, v23
	v_exp_f32_e32 v24, v24
	v_exp_f32_e32 v25, v25
	v_add_u32_e32 v34, 0xa0, v164
	v_mad_i64_i32 v[34:35], s[28:29], v34, s21, v[142:143]
	v_lshl_add_u64 v[34:35], v[34:35], 0, v[144:145]
	v_pk_fma_f32 v[30:31], v[30:31], v[170:171], v[170:171] op_sel_hi:[1,0,0]
	v_pk_fma_f32 v[32:33], v[32:33], v[170:171], v[170:171] op_sel_hi:[1,0,0]
	v_pk_fma_f32 v[22:23], v[22:23], v[170:171], v[170:171] op_sel_hi:[1,0,0]
	v_pk_fma_f32 v[24:25], v[24:25], v[170:171], v[170:171] op_sel_hi:[1,0,0]
	v_rcp_f32_e32 v30, v30
	v_rcp_f32_e32 v31, v31
	v_rcp_f32_e32 v32, v32
	v_rcp_f32_e32 v33, v33
	v_rcp_f32_e32 v22, v22
	v_rcp_f32_e32 v23, v23
	v_rcp_f32_e32 v24, v24
	v_rcp_f32_e32 v25, v25
	v_pk_mul_f32 v[26:27], v[26:27], v[30:31]
	v_pk_mul_f32 v[28:29], v[28:29], v[32:33]
	v_pk_mul_f32 v[22:23], v[18:19], v[22:23]
	v_pk_mul_f32 v[24:25], v[20:21], v[24:25]
	v_cvt_pk_bf16_f32 v18, v26, v27
	v_cvt_pk_bf16_f32 v19, v28, v29
	v_cvt_pk_bf16_f32 v20, v22, v23
	v_cvt_pk_bf16_f32 v21, v24, v25
	global_store_dwordx4 v[34:35], v[18:21], off sc1
	s_nop 1
	v_cvt_f32_u32_e32 v158, v158
	v_fmamk_f32 v170, v158, 0x34800000, v228
	v_rsq_f32_e32 v158, v170
	v_pk_mul_f32 v[10:11], v[14:15], v[10:11]
	v_pk_mul_f32 v[12:13], v[16:17], v[12:13]
	v_pk_mul_f32 v[2:3], v[6:7], v[2:3]
	v_pk_mul_f32 v[4:5], v[8:9], v[4:5]
	v_mul_f32_e32 v172, 0xbfb8aa3b, v158
	v_pk_mul_f32 v[14:15], v[14:15], v[172:173] op_sel_hi:[1,0]
	v_pk_mul_f32 v[16:17], v[16:17], v[172:173] op_sel_hi:[1,0]
	v_pk_mul_f32 v[6:7], v[6:7], v[172:173] op_sel_hi:[1,0]
	v_pk_mul_f32 v[8:9], v[8:9], v[172:173] op_sel_hi:[1,0]
	v_exp_f32_e32 v14, v14
	v_exp_f32_e32 v15, v15
	v_exp_f32_e32 v16, v16
	v_exp_f32_e32 v17, v17
	v_exp_f32_e32 v6, v6
	v_exp_f32_e32 v7, v7
	v_exp_f32_e32 v8, v8
	v_exp_f32_e32 v9, v9
	v_add_u32_e32 v18, 0xb0, v164
	v_mad_i64_i32 v[18:19], s[28:29], v18, s21, v[142:143]
	v_lshl_add_u64 v[18:19], v[18:19], 0, v[144:145]
	v_pk_fma_f32 v[14:15], v[14:15], v[170:171], v[170:171] op_sel_hi:[1,0,0]
	v_pk_fma_f32 v[16:17], v[16:17], v[170:171], v[170:171] op_sel_hi:[1,0,0]
	v_pk_fma_f32 v[6:7], v[6:7], v[170:171], v[170:171] op_sel_hi:[1,0,0]
	v_pk_fma_f32 v[8:9], v[8:9], v[170:171], v[170:171] op_sel_hi:[1,0,0]
	v_rcp_f32_e32 v14, v14
	v_rcp_f32_e32 v15, v15
	v_rcp_f32_e32 v16, v16
	v_rcp_f32_e32 v17, v17
	v_rcp_f32_e32 v6, v6
	v_rcp_f32_e32 v7, v7
	v_rcp_f32_e32 v8, v8
	v_rcp_f32_e32 v9, v9
	v_pk_mul_f32 v[10:11], v[10:11], v[14:15]
	v_pk_mul_f32 v[12:13], v[12:13], v[16:17]
	v_pk_mul_f32 v[6:7], v[2:3], v[6:7]
	v_pk_mul_f32 v[8:9], v[4:5], v[8:9]
	v_cvt_pk_bf16_f32 v2, v10, v11
	v_cvt_pk_bf16_f32 v3, v12, v13
	v_cvt_pk_bf16_f32 v4, v6, v7
	v_cvt_pk_bf16_f32 v5, v8, v9
	global_store_dwordx4 v[18:19], v[2:5], off sc1
	s_nop 1
	s_mov_b64 s[28:29], -1
	s_cbranch_vccnz .LBB0_359
	s_lshl_b32 s6, s22, 8
	v_add_u32_e32 v2, s6, v1
	v_ashrrev_i32_e32 v3, 31, v2
	v_lshl_add_u64 v[2:3], v[2:3], 2, s[12:13]
	global_load_dword v166, v[2:3], off
	v_add_u32_e32 v2, s6, v148
	v_ashrrev_i32_e32 v3, 31, v2
	v_lshl_add_u64 v[2:3], v[2:3], 2, s[12:13]
	global_load_dword v165, v[2:3], off
	v_add_u32_e32 v2, s6, v149
	v_ashrrev_i32_e32 v3, 31, v2
	v_lshl_add_u64 v[2:3], v[2:3], 2, s[12:13]
	global_load_dword v163, v[2:3], off
	v_add_u32_e32 v2, s6, v150
	v_ashrrev_i32_e32 v3, 31, v2
	v_lshl_add_u64 v[2:3], v[2:3], 2, s[12:13]
	global_load_dword v162, v[2:3], off
	v_add_u32_e32 v2, s6, v151
	v_ashrrev_i32_e32 v3, 31, v2
	v_lshl_add_u64 v[2:3], v[2:3], 2, s[12:13]
	global_load_dword v161, v[2:3], off
	v_add_u32_e32 v2, s6, v152
	v_ashrrev_i32_e32 v3, 31, v2
	v_lshl_add_u64 v[2:3], v[2:3], 2, s[12:13]
	global_load_dword v160, v[2:3], off
	v_add_u32_e32 v2, s6, v153
	v_ashrrev_i32_e32 v3, 31, v2
	v_lshl_add_u64 v[2:3], v[2:3], 2, s[12:13]
	global_load_dword v159, v[2:3], off
	v_add_u32_e32 v2, s6, v154
	v_ashrrev_i32_e32 v3, 31, v2
	v_lshl_add_u64 v[2:3], v[2:3], 2, s[12:13]
	global_load_dword v158, v[2:3], off
	s_andn2_b64 vcc, exec, s[14:15]
	s_cbranch_vccnz .LBB0_358
	s_barrier
	s_branch .LBB0_358

.LBB0_481:
	s_lshl_b32 s6, s41, 5
	s_cmp_eq_u32 s74, 14
	s_cselect_b64 s[4:5], -1, 0
	s_lshl_b32 s7, s55, 8
	s_lshl_b32 s8, s50, 8
	v_lshrrev_b32_e32 v130, 1, v233
	s_or_b32 s6, s7, s6
	s_add_i32 s30, s8, s12
	v_and_or_b32 v220, v130, 24, s6
	v_or_b32_e32 v130, s30, v1
	v_ashrrev_i32_e32 v221, 31, v220
	v_ashrrev_i32_e32 v131, 31, v130
	v_lshl_add_u64 v[150:151], v[220:221], 1, s[80:81]
	v_lshlrev_b64 v[132:133], 11, v[130:131]
	v_lshl_add_u64 v[132:133], v[150:151], 0, v[132:133]
	s_barrier
	global_load_dwordx4 v[198:201], v[132:133], off
	global_load_dwordx4 v[186:189], v[132:133], off offset:256
	v_or_b32_e32 v132, 16, v130
	v_ashrrev_i32_e32 v133, 31, v132
	v_lshlrev_b64 v[132:133], 11, v[132:133]
	v_lshl_add_u64 v[132:133], v[150:151], 0, v[132:133]
	global_load_dwordx4 v[178:181], v[132:133], off
	global_load_dwordx4 v[170:173], v[132:133], off offset:256
	v_or_b32_e32 v132, 32, v130
	v_or_b32_e32 v130, 48, v130
	v_ashrrev_i32_e32 v133, 31, v132
	v_ashrrev_i32_e32 v131, 31, v130
	v_lshlrev_b64 v[132:133], 11, v[132:133]
	v_lshlrev_b64 v[130:131], 11, v[130:131]
	v_lshl_add_u64 v[132:133], v[150:151], 0, v[132:133]
	v_lshl_add_u64 v[130:131], v[150:151], 0, v[130:131]
	global_load_dwordx4 v[162:165], v[132:133], off
	global_load_dwordx4 v[146:149], v[132:133], off offset:256
	global_load_dwordx4 v[134:137], v[130:131], off
	s_nop 0
	global_load_dwordx4 v[130:133], v[130:131], off offset:256
	v_readlane_b32 s100, v254, 20
	v_readlane_b32 s101, v254, 21
	v_add_u32_e32 v166, s30, v1
	v_add_u32_e32 v152, 0x80, v166
	v_ashrrev_i32_e32 v153, 31, v152
	v_lshlrev_b64 v[152:153], 11, v[152:153]
	s_nop 1
	v_lshl_add_u64 v[142:143], v[220:221], 2, s[100:101]
	v_lshl_add_u64 v[152:153], v[150:151], 0, v[152:153]
	global_load_dwordx4 v[154:157], v[142:143], off offset:16
	global_load_dwordx4 v[158:161], v[142:143], off
	global_load_dwordx4 v[138:141], v[142:143], off offset:528
	s_nop 0
	global_load_dwordx4 v[142:145], v[142:143], off offset:512
	s_nop 0
	global_load_dwordx4 v[206:209], v[152:153], off
	global_load_dwordx4 v[202:205], v[152:153], off offset:256
	v_add_u32_e32 v152, 0x90, v166
	v_ashrrev_i32_e32 v153, 31, v152
	v_lshlrev_b64 v[152:153], 11, v[152:153]
	v_lshl_add_u64 v[152:153], v[150:151], 0, v[152:153]
	global_load_dwordx4 v[194:197], v[152:153], off
	global_load_dwordx4 v[190:193], v[152:153], off offset:256
	v_add_u32_e32 v152, 0xa0, v166
	v_ashrrev_i32_e32 v153, 31, v152
	v_lshlrev_b64 v[152:153], 11, v[152:153]
	v_lshl_add_u64 v[152:153], v[150:151], 0, v[152:153]
	global_load_dwordx4 v[182:185], v[152:153], off
	global_load_dwordx4 v[174:177], v[152:153], off offset:256
	v_add_u32_e32 v152, 0xb0, v166
	v_ashrrev_i32_e32 v153, 31, v152
	v_lshlrev_b64 v[152:153], 11, v[152:153]
	v_lshl_add_u64 v[150:151], v[150:151], 0, v[152:153]
	global_load_dwordx4 v[166:169], v[150:151], off
	s_nop 0
	global_load_dwordx4 v[150:153], v[150:151], off offset:256
	s_xor_b64 s[6:7], s[24:25], -1
	s_or_b64 s[4:5], s[4:5], s[6:7]
	s_and_b64 vcc, exec, s[4:5]
	s_cbranch_vccnz .LBB0_498
	v_or_b32_e32 v222, s13, v218
	v_cmp_eq_u32_e32 vcc, 0, v222
	s_and_saveexec_b64 s[4:5], vcc
	s_cbranch_execz .LBB0_497
	v_readlane_b32 s7, v254, 9
	s_getreg_b32 s6, hwreg(HW_REG_XCC_ID, 0, 4)
	s_nop 0
	v_mov_b32_e32 v222, s7
	v_readlane_b32 s7, v254, 10
	ds_read_b32 v222, v222
	s_nop 0
	v_mov_b32_e32 v223, s7
	ds_read_b32 v223, v223
	s_waitcnt lgkmcnt(0)
	v_cmp_ne_u32_e32 vcc, 0, v223
	s_cbranch_vccnz .LBB0_496
	s_lshl_b32 s6, s6, 8
	s_and_b32 s6, s6, 0xf00
	s_add_u32 s6, s0, s6
	s_addc_u32 s7, s1, 0
	global_load_dword v223, v227, s[6:7] offset:1024 sc1
	s_add_u32 s6, s6, 0x3400
	s_addc_u32 s7, s7, 0
	s_waitcnt vmcnt(0)
	v_cmp_ne_u32_e32 vcc, v223, v222
	s_cbranch_vccnz .LBB0_496
	s_add_u32 s22, s0, 0x1200
	s_addc_u32 s23, s1, 0
	s_mov_b32 s9, 1
	s_branch .LBB0_487

.LBB0_489:
	global_load_dword v223, v0, s[6:7] sc1
	s_add_i32 s9, s9, 1
	s_mov_b64 s[26:27], -1
	s_waitcnt vmcnt(0)
	v_cmp_ne_u32_e64 s[24:25], v223, v222
	s_branch .LBB0_486
.LBB0_490:
	global_load_dword v223, v0, s[22:23] sc1
	s_waitcnt vmcnt(0)
	v_cmp_eq_u32_e32 vcc, 0, v223
	s_cbranch_vccnz .LBB0_492
	s_mov_b64 s[26:27], -1
	s_branch .LBB0_486

.LBB0_494:
	s_andn2_b64 vcc, exec, s[26:27]
	s_cbranch_vccz .LBB0_496
	v_mov_b64_e32 v[222:223], s[22:23]
	flat_atomic_add v[222:223], v226

.LBB0_498:
	v_lshlrev_b32_e32 v222, 2, v218
	v_xor_b32_e32 v236, 64, v222
	v_xor_b32_e32 v237, 0x80, v222
	s_lshl_b32 s6, s41, 2
	v_cmp_gt_u32_e64 s[4:5], 16, v218
	s_add_i32 s9, s6, 0
	s_lshl_b32 s22, s40, 10
	s_add_i32 s22, s9, s22
	v_lshl_add_u32 v224, v1, 4, s22
	v_mul_f32_e32 v244, v127, v127
	v_mul_f32_e32 v225, v129, v129
	v_fmac_f32_e32 v244, v126, v126
	v_fmac_f32_e32 v225, v128, v128
	v_add_f32_e32 v244, v244, v225
	v_mul_f32_e32 v223, v123, v123
	v_mul_f32_e32 v225, v125, v125
	v_fmac_f32_e32 v223, v122, v122
	v_fmac_f32_e32 v225, v124, v124
	v_add_f32_e32 v223, v223, v225
	v_add_f32_e32 v244, v223, v244
	v_mul_f32_e32 v223, v119, v119
	v_mul_f32_e32 v225, v121, v121
	v_fmac_f32_e32 v223, v118, v118
	v_fmac_f32_e32 v225, v120, v120
	v_add_f32_e32 v223, v223, v225
	v_add_f32_e32 v244, v223, v244
	v_mul_f32_e32 v223, v115, v115
	v_mul_f32_e32 v225, v117, v117
	v_fmac_f32_e32 v223, v114, v114
	v_fmac_f32_e32 v225, v116, v116
	v_add_f32_e32 v223, v223, v225
	v_add_f32_e32 v244, v223, v244
	v_mul_f32_e32 v245, v111, v111
	v_mul_f32_e32 v225, v113, v113
	v_fmac_f32_e32 v245, v110, v110
	v_fmac_f32_e32 v225, v112, v112
	v_add_f32_e32 v245, v245, v225
	v_mul_f32_e32 v223, v107, v107
	v_mul_f32_e32 v225, v109, v109
	v_fmac_f32_e32 v223, v106, v106
	v_fmac_f32_e32 v225, v108, v108
	v_add_f32_e32 v223, v223, v225
	v_add_f32_e32 v245, v223, v245
	v_mul_f32_e32 v223, v103, v103
	v_mul_f32_e32 v225, v105, v105
	v_fmac_f32_e32 v223, v102, v102
	v_fmac_f32_e32 v225, v104, v104
	v_add_f32_e32 v223, v223, v225
	v_add_f32_e32 v245, v223, v245
	v_mul_f32_e32 v223, v99, v99
	v_mul_f32_e32 v225, v101, v101
	v_fmac_f32_e32 v223, v98, v98
	v_fmac_f32_e32 v225, v100, v100
	v_add_f32_e32 v223, v223, v225
	v_add_f32_e32 v245, v223, v245
	v_mul_f32_e32 v246, v95, v95
	v_mul_f32_e32 v225, v97, v97
	v_fmac_f32_e32 v246, v94, v94
	v_fmac_f32_e32 v225, v96, v96
	v_add_f32_e32 v246, v246, v225
	v_mul_f32_e32 v223, v91, v91
	v_mul_f32_e32 v225, v93, v93
	v_fmac_f32_e32 v223, v90, v90
	v_fmac_f32_e32 v225, v92, v92
	v_add_f32_e32 v223, v223, v225
	v_add_f32_e32 v246, v223, v246
	v_mul_f32_e32 v223, v87, v87
	v_mul_f32_e32 v225, v89, v89
	v_fmac_f32_e32 v223, v86, v86
	v_fmac_f32_e32 v225, v88, v88
	v_add_f32_e32 v223, v223, v225
	v_add_f32_e32 v246, v223, v246
	v_mul_f32_e32 v223, v83, v83
	v_mul_f32_e32 v225, v85, v85
	v_fmac_f32_e32 v223, v82, v82
	v_fmac_f32_e32 v225, v84, v84
	v_add_f32_e32 v223, v223, v225
	v_add_f32_e32 v246, v223, v246
	v_mul_f32_e32 v247, v79, v79
	v_mul_f32_e32 v225, v81, v81
	v_fmac_f32_e32 v247, v78, v78
	v_fmac_f32_e32 v225, v80, v80
	v_add_f32_e32 v247, v247, v225
	v_mul_f32_e32 v223, v75, v75
	v_mul_f32_e32 v225, v77, v77
	v_fmac_f32_e32 v223, v74, v74
	v_fmac_f32_e32 v225, v76, v76
	v_add_f32_e32 v223, v223, v225
	v_add_f32_e32 v247, v223, v247
	v_mul_f32_e32 v223, v71, v71
	v_mul_f32_e32 v225, v73, v73
	v_fmac_f32_e32 v223, v70, v70
	v_fmac_f32_e32 v225, v72, v72
	v_add_f32_e32 v223, v223, v225
	v_add_f32_e32 v247, v223, v247
	v_mul_f32_e32 v223, v67, v67
	v_mul_f32_e32 v225, v69, v69
	v_fmac_f32_e32 v223, v66, v66
	v_fmac_f32_e32 v225, v68, v68
	v_add_f32_e32 v223, v223, v225
	v_add_f32_e32 v247, v223, v247
	ds_bpermute_b32 v248, v236, v244
	ds_bpermute_b32 v249, v236, v245
	ds_bpermute_b32 v250, v236, v246
	ds_bpermute_b32 v251, v236, v247
	s_waitcnt lgkmcnt(0)
	v_add_f32_e32 v244, v244, v248
	v_add_f32_e32 v245, v245, v249
	v_add_f32_e32 v246, v246, v250
	v_add_f32_e32 v247, v247, v251
	ds_bpermute_b32 v248, v237, v244
	ds_bpermute_b32 v249, v237, v245
	ds_bpermute_b32 v250, v237, v246
	ds_bpermute_b32 v251, v237, v247
	s_waitcnt lgkmcnt(0)
	s_and_saveexec_b64 s[6:7], s[4:5]
	v_add_f32_e32 v244, v244, v248
	v_add_f32_e32 v245, v245, v249
	v_add_f32_e32 v246, v246, v250
	v_add_f32_e32 v247, v247, v251
	ds_write_b32 v224, v244
	ds_write_b32 v224, v245 offset:256
	ds_write_b32 v224, v246 offset:512
	ds_write_b32 v224, v247 offset:768
	s_or_b64 exec, exec, s[6:7]
	v_mul_f32_e32 v244, v63, v63
	v_mul_f32_e32 v225, v65, v65
	v_fmac_f32_e32 v244, v62, v62
	v_fmac_f32_e32 v225, v64, v64
	v_add_f32_e32 v244, v244, v225
	v_mul_f32_e32 v223, v59, v59
	v_mul_f32_e32 v225, v61, v61
	v_fmac_f32_e32 v223, v58, v58
	v_fmac_f32_e32 v225, v60, v60
	v_add_f32_e32 v223, v223, v225
	v_add_f32_e32 v244, v223, v244
	v_mul_f32_e32 v223, v55, v55
	v_mul_f32_e32 v225, v57, v57
	v_fmac_f32_e32 v223, v54, v54
	v_fmac_f32_e32 v225, v56, v56
	v_add_f32_e32 v223, v223, v225
	v_add_f32_e32 v244, v223, v244
	v_mul_f32_e32 v223, v51, v51
	v_mul_f32_e32 v225, v53, v53
	v_fmac_f32_e32 v223, v50, v50
	v_fmac_f32_e32 v225, v52, v52
	v_add_f32_e32 v223, v223, v225
	v_add_f32_e32 v244, v223, v244
	v_mul_f32_e32 v245, v47, v47
	v_mul_f32_e32 v225, v49, v49
	v_fmac_f32_e32 v245, v46, v46
	v_fmac_f32_e32 v225, v48, v48
	v_add_f32_e32 v245, v245, v225
	v_mul_f32_e32 v223, v43, v43
	v_mul_f32_e32 v225, v45, v45
	v_fmac_f32_e32 v223, v42, v42
	v_fmac_f32_e32 v225, v44, v44
	v_add_f32_e32 v223, v223, v225
	v_add_f32_e32 v245, v223, v245
	v_mul_f32_e32 v223, v39, v39
	v_mul_f32_e32 v225, v41, v41
	v_fmac_f32_e32 v223, v38, v38
	v_fmac_f32_e32 v225, v40, v40
	v_add_f32_e32 v223, v223, v225
	v_add_f32_e32 v245, v223, v245
	v_mul_f32_e32 v223, v35, v35
	v_mul_f32_e32 v225, v37, v37
	v_fmac_f32_e32 v223, v34, v34
	v_fmac_f32_e32 v225, v36, v36
	v_add_f32_e32 v223, v223, v225
	v_add_f32_e32 v245, v223, v245
	v_mul_f32_e32 v246, v31, v31
	v_mul_f32_e32 v225, v33, v33
	v_fmac_f32_e32 v246, v30, v30
	v_fmac_f32_e32 v225, v32, v32
	v_add_f32_e32 v246, v246, v225
	v_mul_f32_e32 v223, v27, v27
	v_mul_f32_e32 v225, v29, v29
	v_fmac_f32_e32 v223, v26, v26
	v_fmac_f32_e32 v225, v28, v28
	v_add_f32_e32 v223, v223, v225
	v_add_f32_e32 v246, v223, v246
	v_mul_f32_e32 v223, v23, v23
	v_mul_f32_e32 v225, v25, v25
	v_fmac_f32_e32 v223, v22, v22
	v_fmac_f32_e32 v225, v24, v24
	v_add_f32_e32 v223, v223, v225
	v_add_f32_e32 v246, v223, v246
	v_mul_f32_e32 v223, v19, v19
	v_mul_f32_e32 v225, v21, v21
	v_fmac_f32_e32 v223, v18, v18
	v_fmac_f32_e32 v225, v20, v20
	v_add_f32_e32 v223, v223, v225
	v_add_f32_e32 v246, v223, v246
	v_mul_f32_e32 v247, v15, v15
	v_mul_f32_e32 v225, v17, v17
	v_fmac_f32_e32 v247, v14, v14
	v_fmac_f32_e32 v225, v16, v16
	v_add_f32_e32 v247, v247, v225
	v_mul_f32_e32 v223, v11, v11
	v_mul_f32_e32 v225, v13, v13
	v_fmac_f32_e32 v223, v10, v10
	v_fmac_f32_e32 v225, v12, v12
	v_add_f32_e32 v223, v223, v225
	v_add_f32_e32 v247, v223, v247
	v_mul_f32_e32 v223, v7, v7
	v_mul_f32_e32 v225, v9, v9
	v_fmac_f32_e32 v223, v6, v6
	v_fmac_f32_e32 v225, v8, v8
	v_add_f32_e32 v223, v223, v225
	v_add_f32_e32 v247, v223, v247
	v_mul_f32_e32 v223, v3, v3
	v_mul_f32_e32 v225, v5, v5
	v_fmac_f32_e32 v223, v2, v2
	v_fmac_f32_e32 v225, v4, v4
	v_add_f32_e32 v223, v223, v225
	v_add_f32_e32 v247, v223, v247
	ds_bpermute_b32 v248, v236, v244
	ds_bpermute_b32 v249, v236, v245
	ds_bpermute_b32 v250, v236, v246
	ds_bpermute_b32 v251, v236, v247
	s_waitcnt lgkmcnt(0)
	v_add_f32_e32 v244, v244, v248
	v_add_f32_e32 v245, v245, v249
	v_add_f32_e32 v246, v246, v250
	v_add_f32_e32 v247, v247, v251
	ds_bpermute_b32 v248, v237, v244
	ds_bpermute_b32 v249, v237, v245
	ds_bpermute_b32 v250, v237, v246
	ds_bpermute_b32 v251, v237, v247
	s_waitcnt lgkmcnt(0)
	s_and_saveexec_b64 s[6:7], s[4:5]
	v_add_f32_e32 v244, v244, v248
	v_add_f32_e32 v245, v245, v249
	v_add_f32_e32 v246, v246, v250
	v_add_f32_e32 v247, v247, v251
	ds_write_b32 v224, v244 offset:2048
	ds_write_b32 v224, v245 offset:2304
	ds_write_b32 v224, v246 offset:2560
	ds_write_b32 v224, v247 offset:2816
	s_or_b64 exec, exec, s[6:7]
	s_and_b64 s[6:7], s[16:17], exec
	s_cselect_b32 s9, 2, 3
	s_and_b64 s[6:7], s[20:21], exec
	s_cselect_b32 s9, 1, s9
	s_and_b64 s[6:7], exec, s[18:19]
	v_readlane_b32 s6, v254, 51
	s_cselect_b32 s9, 0, s9
	s_lshl_b32 s6, s6, 1
	s_add_i32 s16, s6, 6
	s_lshl_b32 s17, s9, 1
	s_and_b64 s[6:7], s[10:11], exec
	s_cselect_b32 s6, s17, s16
	s_lshl_b32 s6, s6, 18
	v_and_b32_e32 v222, 31, v233
	s_and_b32 s6, s6, 0x180000
	v_lshl_or_b32 v238, s13, 5, v222
	s_add_u32 s6, s0, s6
	v_add_u32_e32 v222, s8, v238
	s_addc_u32 s7, s1, 0
	s_waitcnt lgkmcnt(0)
	s_barrier
	s_waitcnt lgkmcnt(0)
	v_ashrrev_i32_e32 v223, 31, v222
	v_lshl_add_u64 v[222:223], v[222:223], 3, s[6:7]
	s_mov_b64 s[6:7], 0x100000
	v_lshl_add_u64 v[222:223], v[222:223], 0, s[6:7]
	v_cmp_gt_u32_e64 s[6:7], 32, v218
	s_and_saveexec_b64 s[16:17], s[6:7]
	s_cbranch_execz .LBB0_516
	v_lshl_add_u32 v224, v238, 4, 0
	ds_read_b128 v[240:243], v224
	s_mov_b32 s13, 0x3d000000
	s_waitcnt lgkmcnt(0)
	v_add_f32_e32 v224, v240, v241
	v_add_f32_e32 v225, v242, v243
	v_add_f32_e32 v224, v224, v225
	v_min_f32_e32 v224, 0x4f6e6b28, v224
	v_mul_f32_e32 v225, 0x3d000000, v224
	v_floor_f32_e32 v225, v225
	v_fma_f32 v224, v224, s13, -v225
	v_mul_f32_e32 v224, 0x4e000000, v224
	v_cvt_u32_f32_e32 v224, v224
	v_cvt_u32_f32_e32 v225, v225
	v_lshl_or_b32 v224, v224, 3, 1
	global_atomic_add_x2 v[222:223], v[224:225], off
.LBB0_516:
	s_or_b64 exec, exec, s[16:17]
	v_mov_b32_e32 v224, 4
	v_mov_b32_e32 v225, 0
	s_mov_b32 s13, 0x9c40
	s_branch .LBB0_518

.LBB0_518:
	s_and_saveexec_b64 s[16:17], s[6:7]
	s_cbranch_execz .LBB0_520
	global_load_dwordx2 v[224:225], v[222:223], off sc1
.LBB0_520:
	s_or_b64 exec, exec, s[16:17]
	s_waitcnt vmcnt(0)
	v_and_b32_e32 v230, 7, v224
	v_cmp_ne_u32_e32 vcc, 4, v230
	s_cbranch_vccz .LBB0_517
	s_sleep 2
	s_and_saveexec_b64 s[16:17], s[6:7]
	s_cbranch_execz .LBB0_523
	global_load_dwordx2 v[224:225], v[222:223], off sc1
	s_waitcnt vmcnt(0)
	v_and_b32_e32 v230, 7, v224
.LBB0_523:
	s_or_b64 exec, exec, s[16:17]
	v_cmp_ne_u32_e32 vcc, 4, v230
	s_cbranch_vccz .LBB0_517
	s_sleep 2
	s_and_saveexec_b64 s[16:17], s[6:7]
	s_cbranch_execz .LBB0_526
	global_load_dwordx2 v[224:225], v[222:223], off sc1
	s_waitcnt vmcnt(0)
	v_and_b32_e32 v230, 7, v224

.LBB0_532:
	s_or_b64 exec, exec, s[16:17]
	v_cmp_ne_u32_e32 vcc, 4, v230
	s_cbranch_vccz .LBB0_517
	s_add_i32 s13, s13, -5
	s_cmp_eq_u32 s13, 0
	s_sleep 2
	s_cselect_b64 s[16:17], -1, 0
	s_and_b64 vcc, exec, s[16:17]
	s_cbranch_vccz .LBB0_518
.LBB0_534:
	s_and_saveexec_b64 s[16:17], s[6:7]
	s_cbranch_execz .LBB0_536
	v_lshrrev_b32_e32 v223, 3, v224
	v_cvt_f32_u32_e32 v222, v225
	v_cvt_f32_u32_e32 v223, v223
	s_mov_b32 s6, 0xf800000
	v_fmac_f32_e32 v223, 0x4e000000, v222
	v_mul_f32_e32 v222, 0x33800000, v223
	v_fmamk_f32 v222, v222, 0x3a800000, v228
	v_mul_f32_e32 v223, 0x4f800000, v222
	v_cmp_gt_f32_e32 vcc, s6, v222
	s_nop 1
	v_cndmask_b32_e32 v222, v222, v223, vcc
	v_sqrt_f32_e32 v223, v222
	s_nop 0
	v_add_u32_e32 v224, -1, v223
	v_add_u32_e32 v225, 1, v223
	v_fma_f32 v230, -v224, v223, v222
	v_fma_f32 v231, -v225, v223, v222
	v_cmp_ge_f32_e64 s[6:7], 0, v230
	s_nop 1
	v_cndmask_b32_e64 v223, v223, v224, s[6:7]
	v_cmp_lt_f32_e64 s[6:7], 0, v231
	s_nop 1
	v_cndmask_b32_e64 v223, v223, v225, s[6:7]
	v_mul_f32_e32 v224, 0x37800000, v223
	v_cndmask_b32_e32 v223, v223, v224, vcc
	v_mov_b32_e32 v224, 0x260
	v_cmp_class_f32_e32 vcc, v222, v224
	s_nop 1
	v_cndmask_b32_e32 v222, v223, v222, vcc
	v_div_scale_f32 v223, s[6:7], v222, v222, 1.0
	v_rcp_f32_e32 v224, v223
	s_nop 0
	v_fma_f32 v225, -v223, v224, 1.0
	v_fmac_f32_e32 v224, v225, v224
	v_div_scale_f32 v225, vcc, 1.0, v222, 1.0
	v_mul_f32_e32 v230, v225, v224
	v_fma_f32 v231, -v223, v230, v225
	v_fmac_f32_e32 v230, v231, v224
	v_fma_f32 v223, -v223, v230, v225
	v_div_fmas_f32 v223, v223, v224, v230
	v_div_fixup_f32 v222, v223, v222, 1.0
	v_lshl_add_u32 v223, v238, 2, 0
	ds_write_b32 v223, v222 offset:4096
.LBB0_536:
	s_or_b64 exec, exec, s[16:17]
	v_readlane_b32 s44, v254, 14
	v_readlane_b32 s50, v254, 20
	v_readlane_b32 s51, v254, 21
	s_waitcnt lgkmcnt(0)
	s_barrier
	s_add_u32 s13, s0, 0x8200000
	s_addc_u32 s16, s1, 0
	s_and_b64 s[6:7], s[10:11], exec
	s_cselect_b32 s17, s81, s16
	s_cselect_b32 s16, s80, s13
	s_add_u32 s13, s0, 0x4a00000
	s_addc_u32 s20, s1, 0
	s_and_b64 s[6:7], s[10:11], exec
	v_readlane_b32 s6, v254, 49
	v_readlane_b32 s45, v254, 15
	v_readlane_b32 s46, v254, 16
	v_readlane_b32 s47, v254, 17
	v_readlane_b32 s48, v254, 18
	v_readlane_b32 s49, v254, 19
	v_readlane_b32 s52, v254, 22
	v_readlane_b32 s53, v254, 23
	v_readlane_b32 s54, v254, 24
	v_readlane_b32 s55, v254, 25
	v_readlane_b32 s56, v254, 26
	v_readlane_b32 s57, v254, 27
	v_readlane_b32 s58, v254, 28
	v_readlane_b32 s59, v254, 29
	v_readlane_b32 s7, v254, 50
	v_lshl_add_u32 v238, v235, 2, 0
	s_load_dwordx16 s[44:59], s[6:7], 0x40
	v_lshlrev_b32_e32 v240, 16, v200
	v_and_b32_e32 v241, 0xffff0000, v200
	ds_read_b32 v200, v238 offset:4096
	v_add_u32_e32 v222, s8, v235
	v_ashrrev_i32_e32 v223, 31, v222
	v_lshlrev_b64 v[224:225], 10, v[222:223]
	s_waitcnt lgkmcnt(0)
	s_mov_b64 s[44:45], s[48:49]
	v_lshlrev_b32_e32 v230, 16, v198
	v_and_b32_e32 v231, 0xffff0000, v198
	v_lshlrev_b32_e32 v198, 16, v199
	v_and_b32_e32 v199, 0xffff0000, v199
	v_lshlrev_b32_e32 v242, 16, v201
	v_and_b32_e32 v243, 0xffff0000, v201
	v_lshl_add_u64 v[224:225], v[224:225], 0, v[220:221]
	s_mov_b64 s[46:47], s[50:51]
	s_mov_b64 s[48:49], s[52:53]
	s_mov_b64 s[50:51], s[54:55]
	s_mov_b64 s[52:53], s[56:57]
	s_mov_b64 s[54:55], s[58:59]
	v_pk_mul_f32 v[128:129], v[128:129], v[200:201] op_sel_hi:[1,0]
	v_pk_mul_f32 v[126:127], v[126:127], v[200:201] op_sel_hi:[1,0]
	v_pk_mul_f32 v[124:125], v[124:125], v[200:201] op_sel_hi:[1,0]
	v_pk_mul_f32 v[122:123], v[122:123], v[200:201] op_sel_hi:[1,0]
	s_mov_b64 s[18:19], -1
	s_cselect_b32 s7, s55, s20
	s_cselect_b32 s6, s54, s13
	s_and_b64 vcc, exec, s[14:15]
	v_pk_fma_f32 v[122:123], v[154:155], v[122:123], v[240:241]
	v_pk_fma_f32 v[126:127], v[158:159], v[126:127], v[230:231]
	v_pk_fma_f32 v[128:129], v[160:161], v[128:129], v[198:199]
	v_pk_fma_f32 v[124:125], v[156:157], v[124:125], v[242:243]
	v_lshl_add_u64 v[198:199], v[224:225], 1, s[16:17]
	s_cbranch_vccz .LBB0_538
	v_cvt_pk_bf16_f32 v240, v126, v127
	v_cvt_pk_bf16_f32 v241, v128, v129
	v_cvt_pk_bf16_f32 v242, v122, v123
	v_cvt_pk_bf16_f32 v243, v124, v125
	s_mov_b64 s[18:19], 0
	global_store_dwordx4 v[198:199], v[240:243], off sc1
	s_nop 1

.LBB0_540:
	v_mov_b32_e32 v201, v200
	v_mov_b32_e32 v242, v200
	v_mov_b32_e32 v243, v200
	v_lshlrev_b32_e32 v230, 16, v186
	v_and_b32_e32 v231, 0xffff0000, v186
	v_lshlrev_b32_e32 v186, 16, v187
	v_and_b32_e32 v187, 0xffff0000, v187
	v_lshlrev_b32_e32 v240, 16, v188
	v_and_b32_e32 v241, 0xffff0000, v188
	v_lshlrev_b32_e32 v188, 16, v189
	v_and_b32_e32 v189, 0xffff0000, v189
	v_pk_mul_f32 v[120:121], v[120:121], v[242:243]
	v_pk_mul_f32 v[118:119], v[118:119], v[200:201]
	v_pk_mul_f32 v[116:117], v[116:117], v[242:243]
	v_pk_mul_f32 v[114:115], v[114:115], v[200:201]
	v_pk_fma_f32 v[120:121], v[144:145], v[120:121], v[186:187]
	v_pk_fma_f32 v[118:119], v[142:143], v[118:119], v[230:231]
	v_pk_fma_f32 v[116:117], v[140:141], v[116:117], v[188:189]
	v_pk_fma_f32 v[114:115], v[138:139], v[114:115], v[240:241]
	s_mov_b64 s[18:19], -1
	s_and_b64 vcc, exec, s[14:15]
	s_cbranch_vccz .LBB0_542
	v_cvt_pk_bf16_f32 v186, v118, v119
	v_cvt_pk_bf16_f32 v187, v120, v121
	v_cvt_pk_bf16_f32 v188, v114, v115
	v_cvt_pk_bf16_f32 v189, v116, v117
	v_lshl_add_u64 v[198:199], v[198:199], 0, s[2:3]
	global_store_dwordx4 v[198:199], v[186:189], off sc1
	s_nop 1
	s_mov_b64 s[18:19], 0

.LBB0_568:
	s_nop 1
	ds_read_b32 v130, v238 offset:4608
	v_add_u32_e32 v132, 0x80, v222
	v_ashrrev_i32_e32 v133, 31, v132
	v_lshlrev_b64 v[132:133], 10, v[132:133]
	v_lshl_add_u64 v[134:135], v[132:133], 0, v[220:221]
	v_lshlrev_b32_e32 v132, 16, v206
	v_and_b32_e32 v133, 0xffff0000, v206
	v_lshlrev_b32_e32 v136, 16, v207
	v_and_b32_e32 v137, 0xffff0000, v207
	v_lshlrev_b32_e32 v146, 16, v208
	v_and_b32_e32 v147, 0xffff0000, v208
	v_lshlrev_b32_e32 v148, 16, v209
	v_and_b32_e32 v149, 0xffff0000, v209
	s_waitcnt lgkmcnt(0)
	v_pk_mul_f32 v[62:63], v[62:63], v[130:131] op_sel_hi:[1,0]
	v_pk_mul_f32 v[64:65], v[64:65], v[130:131] op_sel_hi:[1,0]
	v_pk_mul_f32 v[58:59], v[58:59], v[130:131] op_sel_hi:[1,0]
	v_pk_mul_f32 v[60:61], v[60:61], v[130:131] op_sel_hi:[1,0]
	v_pk_fma_f32 v[64:65], v[160:161], v[64:65], v[136:137]
	v_pk_fma_f32 v[62:63], v[158:159], v[62:63], v[132:133]
	v_pk_fma_f32 v[60:61], v[156:157], v[60:61], v[148:149]
	v_pk_fma_f32 v[58:59], v[154:155], v[58:59], v[146:147]
	s_mov_b64 s[18:19], -1
	s_and_b64 vcc, exec, s[14:15]
	v_lshl_add_u64 v[132:133], v[134:135], 1, s[16:17]
	s_cbranch_vccz .LBB0_570
	v_cvt_pk_bf16_f32 v146, v62, v63
	v_cvt_pk_bf16_f32 v147, v64, v65
	v_cvt_pk_bf16_f32 v148, v58, v59
	v_cvt_pk_bf16_f32 v149, v60, v61
	s_mov_b64 s[18:19], 0
	global_store_dwordx4 v[132:133], v[146:149], off sc1
	s_nop 1

.LBB0_572:
	v_mov_b32_e32 v131, v130
	v_mov_b32_e32 v164, v130
	v_mov_b32_e32 v165, v130
	v_lshlrev_b32_e32 v136, 16, v202
	v_and_b32_e32 v137, 0xffff0000, v202
	v_lshlrev_b32_e32 v146, 16, v203
	v_and_b32_e32 v147, 0xffff0000, v203
	v_lshlrev_b32_e32 v148, 16, v204
	v_and_b32_e32 v149, 0xffff0000, v204
	v_lshlrev_b32_e32 v162, 16, v205
	v_and_b32_e32 v163, 0xffff0000, v205
	v_pk_mul_f32 v[56:57], v[56:57], v[164:165]
	v_pk_mul_f32 v[54:55], v[54:55], v[130:131]
	v_pk_mul_f32 v[52:53], v[52:53], v[164:165]
	v_pk_mul_f32 v[50:51], v[50:51], v[130:131]
	v_pk_fma_f32 v[56:57], v[144:145], v[56:57], v[146:147]
	v_pk_fma_f32 v[54:55], v[142:143], v[54:55], v[136:137]
	v_pk_fma_f32 v[52:53], v[140:141], v[52:53], v[162:163]
	v_pk_fma_f32 v[50:51], v[138:139], v[50:51], v[148:149]
	s_mov_b64 s[18:19], -1
	s_and_b64 vcc, exec, s[14:15]
	s_cbranch_vccz .LBB0_574
	v_cvt_pk_bf16_f32 v146, v54, v55
	v_cvt_pk_bf16_f32 v147, v56, v57
	v_cvt_pk_bf16_f32 v148, v50, v51
	v_cvt_pk_bf16_f32 v149, v52, v53
	v_lshl_add_u64 v[130:131], v[132:133], 0, s[2:3]
	global_store_dwordx4 v[130:131], v[146:149], off sc1
	s_nop 1
	s_mov_b64 s[18:19], 0

.LBB0_576:
	s_nop 1
	ds_read_b32 v130, v238 offset:4672
	v_add_u32_e32 v132, 0x90, v222
	v_ashrrev_i32_e32 v133, 31, v132
	v_lshlrev_b64 v[132:133], 10, v[132:133]
	v_lshl_add_u64 v[134:135], v[132:133], 0, v[220:221]
	v_lshlrev_b32_e32 v132, 16, v194
	v_and_b32_e32 v133, 0xffff0000, v194
	v_lshlrev_b32_e32 v136, 16, v195
	v_and_b32_e32 v137, 0xffff0000, v195
	v_lshlrev_b32_e32 v146, 16, v196
	v_and_b32_e32 v147, 0xffff0000, v196
	v_lshlrev_b32_e32 v148, 16, v197
	v_and_b32_e32 v149, 0xffff0000, v197
	s_waitcnt lgkmcnt(0)
	v_pk_mul_f32 v[46:47], v[46:47], v[130:131] op_sel_hi:[1,0]
	v_pk_mul_f32 v[48:49], v[48:49], v[130:131] op_sel_hi:[1,0]
	v_pk_mul_f32 v[42:43], v[42:43], v[130:131] op_sel_hi:[1,0]
	v_pk_mul_f32 v[44:45], v[44:45], v[130:131] op_sel_hi:[1,0]
	v_pk_fma_f32 v[48:49], v[160:161], v[48:49], v[136:137]
	v_pk_fma_f32 v[46:47], v[158:159], v[46:47], v[132:133]
	v_pk_fma_f32 v[44:45], v[156:157], v[44:45], v[148:149]
	v_pk_fma_f32 v[42:43], v[154:155], v[42:43], v[146:147]
	s_mov_b64 s[18:19], -1
	s_and_b64 vcc, exec, s[14:15]
	v_lshl_add_u64 v[132:133], v[134:135], 1, s[16:17]
	s_cbranch_vccz .LBB0_578
	v_cvt_pk_bf16_f32 v146, v46, v47
	v_cvt_pk_bf16_f32 v147, v48, v49
	v_cvt_pk_bf16_f32 v148, v42, v43
	v_cvt_pk_bf16_f32 v149, v44, v45
	s_mov_b64 s[18:19], 0
	global_store_dwordx4 v[132:133], v[146:149], off sc1
	s_nop 1

.LBB0_580:
	v_mov_b32_e32 v131, v130
	v_mov_b32_e32 v164, v130
	v_mov_b32_e32 v165, v130
	v_lshlrev_b32_e32 v136, 16, v190
	v_and_b32_e32 v137, 0xffff0000, v190
	v_lshlrev_b32_e32 v146, 16, v191
	v_and_b32_e32 v147, 0xffff0000, v191
	v_lshlrev_b32_e32 v148, 16, v192
	v_and_b32_e32 v149, 0xffff0000, v192
	v_lshlrev_b32_e32 v162, 16, v193
	v_and_b32_e32 v163, 0xffff0000, v193
	v_pk_mul_f32 v[40:41], v[40:41], v[164:165]
	v_pk_mul_f32 v[38:39], v[38:39], v[130:131]
	v_pk_mul_f32 v[36:37], v[36:37], v[164:165]
	v_pk_mul_f32 v[34:35], v[34:35], v[130:131]
	v_pk_fma_f32 v[40:41], v[144:145], v[40:41], v[146:147]
	v_pk_fma_f32 v[38:39], v[142:143], v[38:39], v[136:137]
	v_pk_fma_f32 v[36:37], v[140:141], v[36:37], v[162:163]
	v_pk_fma_f32 v[34:35], v[138:139], v[34:35], v[148:149]
	s_mov_b64 s[18:19], -1
	s_and_b64 vcc, exec, s[14:15]
	s_cbranch_vccz .LBB0_582
	v_cvt_pk_bf16_f32 v146, v38, v39
	v_cvt_pk_bf16_f32 v147, v40, v41
	v_cvt_pk_bf16_f32 v148, v34, v35
	v_cvt_pk_bf16_f32 v149, v36, v37
	v_lshl_add_u64 v[130:131], v[132:133], 0, s[2:3]
	global_store_dwordx4 v[130:131], v[146:149], off sc1
	s_nop 1
	s_mov_b64 s[18:19], 0

.LBB0_584:
	s_nop 1
	ds_read_b32 v130, v238 offset:4736
	v_add_u32_e32 v132, 0xa0, v222
	v_ashrrev_i32_e32 v133, 31, v132
	v_lshlrev_b64 v[132:133], 10, v[132:133]
	v_lshl_add_u64 v[134:135], v[132:133], 0, v[220:221]
	v_lshlrev_b32_e32 v132, 16, v182
	v_and_b32_e32 v133, 0xffff0000, v182
	v_lshlrev_b32_e32 v136, 16, v183
	v_and_b32_e32 v137, 0xffff0000, v183
	v_lshlrev_b32_e32 v146, 16, v184
	v_and_b32_e32 v147, 0xffff0000, v184
	v_lshlrev_b32_e32 v148, 16, v185
	v_and_b32_e32 v149, 0xffff0000, v185
	s_waitcnt lgkmcnt(0)
	v_pk_mul_f32 v[30:31], v[30:31], v[130:131] op_sel_hi:[1,0]
	v_pk_mul_f32 v[32:33], v[32:33], v[130:131] op_sel_hi:[1,0]
	v_pk_mul_f32 v[26:27], v[26:27], v[130:131] op_sel_hi:[1,0]
	v_pk_mul_f32 v[28:29], v[28:29], v[130:131] op_sel_hi:[1,0]
	v_pk_fma_f32 v[32:33], v[160:161], v[32:33], v[136:137]
	v_pk_fma_f32 v[30:31], v[158:159], v[30:31], v[132:133]
	v_pk_fma_f32 v[28:29], v[156:157], v[28:29], v[148:149]
	v_pk_fma_f32 v[26:27], v[154:155], v[26:27], v[146:147]
	s_mov_b64 s[18:19], -1
	s_and_b64 vcc, exec, s[14:15]
	v_lshl_add_u64 v[132:133], v[134:135], 1, s[16:17]
	s_cbranch_vccz .LBB0_586
	v_cvt_pk_bf16_f32 v146, v30, v31
	v_cvt_pk_bf16_f32 v147, v32, v33
	v_cvt_pk_bf16_f32 v148, v26, v27
	v_cvt_pk_bf16_f32 v149, v28, v29
	s_mov_b64 s[18:19], 0
	global_store_dwordx4 v[132:133], v[146:149], off sc1
	s_nop 1

.LBB0_588:
	v_mov_b32_e32 v131, v130
	v_mov_b32_e32 v164, v130
	v_mov_b32_e32 v165, v130
	v_lshlrev_b32_e32 v136, 16, v174
	v_and_b32_e32 v137, 0xffff0000, v174
	v_lshlrev_b32_e32 v146, 16, v175
	v_and_b32_e32 v147, 0xffff0000, v175
	v_lshlrev_b32_e32 v148, 16, v176
	v_and_b32_e32 v149, 0xffff0000, v176
	v_lshlrev_b32_e32 v162, 16, v177
	v_and_b32_e32 v163, 0xffff0000, v177
	v_pk_mul_f32 v[24:25], v[24:25], v[164:165]
	v_pk_mul_f32 v[22:23], v[22:23], v[130:131]
	v_pk_mul_f32 v[20:21], v[20:21], v[164:165]
	v_pk_mul_f32 v[18:19], v[18:19], v[130:131]
	v_pk_fma_f32 v[24:25], v[144:145], v[24:25], v[146:147]
	v_pk_fma_f32 v[22:23], v[142:143], v[22:23], v[136:137]
	v_pk_fma_f32 v[20:21], v[140:141], v[20:21], v[162:163]
	v_pk_fma_f32 v[18:19], v[138:139], v[18:19], v[148:149]
	s_mov_b64 s[18:19], -1
	s_and_b64 vcc, exec, s[14:15]
	s_cbranch_vccz .LBB0_590
	v_cvt_pk_bf16_f32 v146, v22, v23
	v_cvt_pk_bf16_f32 v147, v24, v25
	v_cvt_pk_bf16_f32 v148, v18, v19
	v_cvt_pk_bf16_f32 v149, v20, v21
	v_lshl_add_u64 v[130:131], v[132:133], 0, s[2:3]
	global_store_dwordx4 v[130:131], v[146:149], off sc1
	s_nop 1
	s_mov_b64 s[18:19], 0

.LBB0_592:
	s_nop 1
	ds_read_b32 v130, v238 offset:4800
	v_add_u32_e32 v132, 0xb0, v222
	v_ashrrev_i32_e32 v133, 31, v132
	v_lshlrev_b64 v[132:133], 10, v[132:133]
	v_lshl_add_u64 v[134:135], v[132:133], 0, v[220:221]
	v_lshlrev_b32_e32 v132, 16, v166
	v_and_b32_e32 v133, 0xffff0000, v166
	v_lshlrev_b32_e32 v136, 16, v167
	v_and_b32_e32 v137, 0xffff0000, v167
	v_lshlrev_b32_e32 v146, 16, v168
	v_and_b32_e32 v147, 0xffff0000, v168
	v_lshlrev_b32_e32 v148, 16, v169
	v_and_b32_e32 v149, 0xffff0000, v169
	s_waitcnt lgkmcnt(0)
	v_pk_mul_f32 v[14:15], v[14:15], v[130:131] op_sel_hi:[1,0]
	v_pk_mul_f32 v[16:17], v[16:17], v[130:131] op_sel_hi:[1,0]
	v_pk_mul_f32 v[10:11], v[10:11], v[130:131] op_sel_hi:[1,0]
	v_pk_mul_f32 v[12:13], v[12:13], v[130:131] op_sel_hi:[1,0]
	v_pk_fma_f32 v[16:17], v[160:161], v[16:17], v[136:137]
	v_pk_fma_f32 v[14:15], v[158:159], v[14:15], v[132:133]
	v_pk_fma_f32 v[12:13], v[156:157], v[12:13], v[148:149]
	v_pk_fma_f32 v[10:11], v[154:155], v[10:11], v[146:147]
	s_mov_b64 s[18:19], -1
	s_and_b64 vcc, exec, s[14:15]
	v_lshl_add_u64 v[132:133], v[134:135], 1, s[16:17]
	s_cbranch_vccz .LBB0_594
	v_cvt_pk_bf16_f32 v146, v14, v15
	v_cvt_pk_bf16_f32 v147, v16, v17
	v_cvt_pk_bf16_f32 v148, v10, v11
	v_cvt_pk_bf16_f32 v149, v12, v13
	s_mov_b64 s[18:19], 0
	global_store_dwordx4 v[132:133], v[146:149], off sc1
	s_nop 1

.LBB0_596:
	v_mov_b32_e32 v131, v130
	v_lshlrev_b32_e32 v136, 16, v150
	v_and_b32_e32 v137, 0xffff0000, v150
	v_lshlrev_b32_e32 v146, 16, v151
	v_and_b32_e32 v147, 0xffff0000, v151
	v_lshlrev_b32_e32 v148, 16, v152
	v_and_b32_e32 v149, 0xffff0000, v152
	v_lshlrev_b32_e32 v150, 16, v153
	v_and_b32_e32 v151, 0xffff0000, v153
	v_mov_b32_e32 v152, v130
	v_mov_b32_e32 v153, v130
	v_pk_mul_f32 v[8:9], v[8:9], v[152:153]
	v_pk_mul_f32 v[6:7], v[6:7], v[130:131]
	v_pk_mul_f32 v[4:5], v[4:5], v[152:153]
	v_pk_mul_f32 v[2:3], v[2:3], v[130:131]
	v_pk_fma_f32 v[8:9], v[144:145], v[8:9], v[146:147]
	v_pk_fma_f32 v[6:7], v[142:143], v[6:7], v[136:137]
	v_pk_fma_f32 v[4:5], v[140:141], v[4:5], v[150:151]
	v_pk_fma_f32 v[2:3], v[138:139], v[2:3], v[148:149]
	s_mov_b64 s[6:7], -1
	s_and_b64 vcc, exec, s[14:15]
	s_cbranch_vccz .LBB0_598
	v_cvt_pk_bf16_f32 v136, v6, v7
	v_cvt_pk_bf16_f32 v137, v8, v9
	v_cvt_pk_bf16_f32 v138, v2, v3
	v_cvt_pk_bf16_f32 v139, v4, v5
	v_lshl_add_u64 v[130:131], v[132:133], 0, s[2:3]
	global_store_dwordx4 v[130:131], v[136:139], off sc1
	s_nop 1
	s_mov_b64 s[6:7], 0
